# weight-conversion passes: the 8 per-item norm-gain loads are issued together with one wait instead of 8 serialized load/wait round trips (15 sites)
# speedup vs baseline: 1.0004x; 1.0004x over previous
;     ...
;     const float* src = W + (size_t)(k0 + 2 * q) * N + n0 + 4 * r16;
;     f32x4 v[16];
; #pragma unroll
;     for (int j = 0; j < 16; ++j) v[j] = *(const f32x4*)(src + (size_t)(8 * (j >> 1) + (j & 1)) * N);
;     if (nscale) { const f32x4 ns = *(const f32x4*)(nscale + n0 + 4 * r16);
; #pragma unroll
;         for (int j = 0; j < 16; ++j) v[j] = v[j] * ns; }
;     if (kscale) {
; #pragma unroll
;         for (int i = 0; i < 8; ++i) { const f32x2 g = *(const f32x2*)(kscale + k0 + 8 * i + 2 * q); v[2 * i] = v[2 * i] * g[0]; v[2 * i + 1] = v[2 * i + 1] * g[1]; } }
; __device__ __forceinline__ void weights_pass(const Args& a, LAS unsigned char* scr, int gw, int NGW, int lane, int pass) {
;     ...
;     for (int it = gw + (pass == 1 ? PER_LAYER : 0); it < (pass == 2 ? PER_LAYER : 2 * PER_LAYER); it += NGW) {
;         const int l = it / PER_LAYER; int r = it % PER_LAYER;
;         { const bool shared = (r >= I_IN + I_OUT / 2 && r < I_IN + I_OUT) || (r >= I_IN + I_OUT + I_QM && r < I_IN + I_OUT + 3 * I_QM);
;           const int ip = (shared || (l == 0 && r < I_IN)) ? 0 : (l == 0 ? 2 : 1);
;           if (ip != pass) continue; }
;         unsigned char* wl = ws + WS_W + (size_t)l * WL_SIZE;
;         if (r < I_IN) { transpose_item<1>(a.in[I_WIN] + (size_t)l * DM * INW, DM, INW, (bf16_t*)(wl + WL_IN), a.in[I_GMIX] + l * DM, nullptr, 0, scr, r, lane); continue; } r -= I_IN;
;         if (r < I_OUT / 2) { transpose_item<0>(a.in[I_WOUT] + (size_t)l * DM * DM, 2048, DM, (bf16_t*)(wl + WL_OUT), nullptr, nullptr, 0, scr, r, lane, DM); continue; } r -= I_OUT / 2;
;         if (r < I_OUT / 2) { transpose_item<0>(a.in[I_WOUT] + (size_t)l * DM * DM + (size_t)2048 * DM, 2048, DM, (bf16_t*)(ws + WS_WLOW) + (size_t)l * DM * 2048, nullptr, nullptr, 0, scr, r, lane); continue; } r -= I_OUT / 2;
;         if (r < I_QM) { transpose_item<0>(a.in[I_WQM] + (size_t)l * DM * MW, DM, MW, (bf16_t*)(wl + WL_Q), a.in[I_GCROSS] + l * DM, nullptr, 0, scr, r, lane); continue; } r -= I_QM;
;         if (r < I_QM) { transpose_item<1>(a.in[I_WKM] + (size_t)l * DM * MW, DM, MW, (bf16_t*)(ws + WS_WKV) + (size_t)l * 1024 * DM, a.in[I_GMEM] + l * DM, nullptr, 0, scr, r, lane); continue; } r -= I_QM;
;         if (r < I_QM) { transpose_item<1>(a.in[I_WVM] + (size_t)l * DM * MW, DM, MW, (bf16_t*)(ws + WS_WKV) + (size_t)l * 1024 * DM, a.in[I_GMEM] + l * DM, nullptr, 512, scr, r, lane); continue; } r -= I_QM;
.LBB0_11:
	s_mul_hi_i32 s0, s46, 0xbfa02fe9
	s_add_i32 s0, s0, s46
	s_lshr_b32 s1, s0, 31
	s_ashr_i32 s0, s0, 15
	s_add_i32 s10, s0, s1
	s_mul_i32 s0, s10, 0xffff5500
	s_add_i32 s49, s46, s0
	s_add_i32 s51, s49, 0xffffe600
	s_cmpk_lt_u32 s51, 0x800
	s_cselect_b64 s[0:1], -1, 0
	s_and_b32 s2, s49, 0xfffffc00
	s_cmpk_eq_i32 s2, 0x2400
	s_cselect_b64 s[12:13], -1, 0
	s_or_b64 s[12:13], s[0:1], s[12:13]
	s_add_i32 s0, s46, 0xaaff
	s_cmp_lt_u32 s0, 0x155ff
	s_cselect_b64 s[14:15], -1, 0
	s_cmpk_gt_i32 s49, 0x11ff
	s_cselect_b64 s[0:1], -1, 0
	s_cmpk_lt_i32 s49, 0x1200
	s_cselect_b64 s[52:53], -1, 0
	s_and_b64 s[14:15], s[14:15], s[52:53]
	s_or_b64 s[12:13], s[12:13], s[14:15]
	s_andn2_b64 vcc, exec, s[12:13]
	s_cbranch_vccnz .LBB0_10
	s_ashr_i32 s11, s10, 31
	s_mul_i32 s8, s10, 0x15000000
	s_mul_hi_i32 s2, s10, 0x15000000
	s_add_u32 s47, s17, s8
	s_addc_u32 s48, s18, s2
	s_mov_b64 s[12:13], -1
	s_and_b64 vcc, exec, s[0:1]
	s_cbranch_vccz .LBB0_35
	s_cmpk_gt_u32 s49, 0x19ff
	s_mov_b64 s[0:1], -1
	s_cbranch_scc0 .LBB0_32
	s_cmpk_gt_u32 s49, 0x21ff
	s_cbranch_scc0 .LBB0_29
	s_lshl_b64 s[12:13], s[10:11], 23
	s_cmpk_gt_u32 s49, 0x23ff
	s_cbranch_scc0 .LBB0_24
	s_add_u32 s52, s19, s12
	s_mul_i32 s0, s10, 0xffd54000
	s_addc_u32 s53, s25, s13
	s_add_i32 s2, s35, s0
	s_and_b32 s54, s2, 0x1c0
	s_cmpk_gt_u32 s49, 0x25ff
	s_mov_b64 s[14:15], -1
	v_cmp_ne_u32_e64 s[0:1], 1, v106
	s_cbranch_scc0 .LBB0_20
	v_readlane_b32 s56, v250, 46
	v_readlane_b32 s64, v250, 54
	v_readlane_b32 s65, v250, 55
	s_add_u32 s14, s64, s12
	s_mul_i32 s8, s10, 0xfffaa800
	s_addc_u32 s15, s65, s13
	s_add_i32 s8, s31, s8
	s_addk_i32 s8, 0xe000
	s_and_b32 s55, s8, 0x7ffc0
	v_or_b32_e32 v2, s55, v74
	v_lshlrev_b32_e32 v2, 11, v2
	v_mov_b32_e32 v3, v71
	v_lshl_add_u64 v[2:3], s[14:15], 0, v[2:3]
	s_lshl_b32 s8, s54, 2
	v_lshl_add_u64 v[2:3], v[2:3], 0, s[8:9]
	v_lshl_add_u64 v[2:3], v[2:3], 0, v[70:71]
	v_add_co_u32_e32 v4, vcc, s39, v2
	global_load_dwordx4 v[58:61], v[2:3], off nt
	global_load_dwordx4 v[62:65], v[2:3], off offset:2048 nt
	v_addc_co_u32_e32 v5, vcc, 0, v3, vcc
	global_load_dwordx4 v[50:53], v[4:5], off nt
	global_load_dwordx4 v[54:57], v[4:5], off offset:2048 nt
	v_add_co_u32_e32 v4, vcc, s40, v2
	v_readlane_b32 s58, v250, 48
	s_nop 0
	v_addc_co_u32_e32 v5, vcc, 0, v3, vcc
	global_load_dwordx4 v[42:45], v[4:5], off nt
	global_load_dwordx4 v[46:49], v[4:5], off offset:2048 nt
	v_add_co_u32_e32 v4, vcc, s41, v2
	v_readlane_b32 s59, v250, 49
	s_nop 0
	v_addc_co_u32_e32 v5, vcc, 0, v3, vcc
	global_load_dwordx4 v[34:37], v[4:5], off nt
	global_load_dwordx4 v[38:41], v[4:5], off offset:2048 nt
	v_add_co_u32_e32 v4, vcc, s42, v2
	v_readlane_b32 s57, v250, 47
	s_nop 0
	v_addc_co_u32_e32 v5, vcc, 0, v3, vcc
	global_load_dwordx4 v[26:29], v[4:5], off nt
	global_load_dwordx4 v[30:33], v[4:5], off offset:2048 nt
	v_add_co_u32_e32 v4, vcc, s43, v2
	v_readlane_b32 s60, v250, 50
	s_nop 0
	v_addc_co_u32_e32 v5, vcc, 0, v3, vcc
	global_load_dwordx4 v[18:21], v[4:5], off nt
	global_load_dwordx4 v[22:25], v[4:5], off offset:2048 nt
	v_add_co_u32_e32 v4, vcc, 0x18000, v2
	v_readlane_b32 s61, v250, 51
	s_nop 0
	v_addc_co_u32_e32 v5, vcc, 0, v3, vcc
	v_add_co_u32_e32 v6, vcc, 0x1c000, v2
	global_load_dwordx4 v[10:13], v[4:5], off nt
	global_load_dwordx4 v[14:17], v[4:5], off offset:2048 nt
	v_addc_co_u32_e32 v7, vcc, 0, v3, vcc
	global_load_dwordx4 v[2:5], v[6:7], off nt
	s_nop 0
	global_load_dwordx4 v[6:9], v[6:7], off offset:2048 nt
	s_and_b64 vcc, exec, s[0:1]
	v_readlane_b32 s62, v250, 52
	v_readlane_b32 s63, v250, 53
	v_readlane_b32 s66, v250, 56
	v_readlane_b32 s67, v250, 57
	v_readlane_b32 s68, v250, 58
	v_readlane_b32 s69, v250, 59
	v_readlane_b32 s70, v250, 60
	v_readlane_b32 s71, v250, 61
	s_cbranch_vccnz .LBB0_19
	s_lshl_b32 s14, s10, 12
	s_ashr_i32 s15, s14, 31
	s_lshl_b64 s[14:15], s[14:15], 2
	s_add_u32 s8, s58, s14
	s_addc_u32 s15, s59, s15
	s_lshl_b32 s14, s55, 2
	s_add_u32 s14, s8, s14
	s_addc_u32 s15, s15, 0
	global_load_dwordx2 v[116:117], v107, s[14:15]
	global_load_dwordx2 v[118:119], v107, s[14:15] offset:32
	global_load_dwordx2 v[120:121], v107, s[14:15] offset:64
	global_load_dwordx2 v[122:123], v107, s[14:15] offset:96
	global_load_dwordx2 v[124:125], v107, s[14:15] offset:128
	global_load_dwordx2 v[126:127], v107, s[14:15] offset:160
	global_load_dwordx2 v[128:129], v107, s[14:15] offset:192
	global_load_dwordx2 v[130:131], v107, s[14:15] offset:224
	s_waitcnt vmcnt(0)
	v_pk_mul_f32 v[60:61], v[60:61], v[116:117] op_sel_hi:[1,0]
	v_pk_mul_f32 v[58:59], v[58:59], v[116:117] op_sel_hi:[1,0]
	v_pk_mul_f32 v[64:65], v[64:65], v[116:117] op_sel:[0,1]
	v_pk_mul_f32 v[62:63], v[62:63], v[116:117] op_sel:[0,1]
	v_pk_mul_f32 v[52:53], v[52:53], v[118:119] op_sel_hi:[1,0]
	v_pk_mul_f32 v[50:51], v[50:51], v[118:119] op_sel_hi:[1,0]
	v_pk_mul_f32 v[56:57], v[56:57], v[118:119] op_sel:[0,1]
	v_pk_mul_f32 v[54:55], v[54:55], v[118:119] op_sel:[0,1]
	v_pk_mul_f32 v[44:45], v[44:45], v[120:121] op_sel_hi:[1,0]
	v_pk_mul_f32 v[42:43], v[42:43], v[120:121] op_sel_hi:[1,0]
	v_pk_mul_f32 v[48:49], v[48:49], v[120:121] op_sel:[0,1]
	v_pk_mul_f32 v[46:47], v[46:47], v[120:121] op_sel:[0,1]
	v_pk_mul_f32 v[36:37], v[36:37], v[122:123] op_sel_hi:[1,0]
	v_pk_mul_f32 v[34:35], v[34:35], v[122:123] op_sel_hi:[1,0]
	v_pk_mul_f32 v[40:41], v[40:41], v[122:123] op_sel:[0,1]
	v_pk_mul_f32 v[38:39], v[38:39], v[122:123] op_sel:[0,1]
	v_pk_mul_f32 v[28:29], v[28:29], v[124:125] op_sel_hi:[1,0]
	v_pk_mul_f32 v[26:27], v[26:27], v[124:125] op_sel_hi:[1,0]
	v_pk_mul_f32 v[32:33], v[32:33], v[124:125] op_sel:[0,1]
	v_pk_mul_f32 v[30:31], v[30:31], v[124:125] op_sel:[0,1]
	v_pk_mul_f32 v[20:21], v[20:21], v[126:127] op_sel_hi:[1,0]
	v_pk_mul_f32 v[18:19], v[18:19], v[126:127] op_sel_hi:[1,0]
	v_pk_mul_f32 v[24:25], v[24:25], v[126:127] op_sel:[0,1]
	v_pk_mul_f32 v[22:23], v[22:23], v[126:127] op_sel:[0,1]
	v_pk_mul_f32 v[12:13], v[12:13], v[128:129] op_sel_hi:[1,0]
	v_pk_mul_f32 v[10:11], v[10:11], v[128:129] op_sel_hi:[1,0]
	v_pk_mul_f32 v[16:17], v[16:17], v[128:129] op_sel:[0,1]
	v_pk_mul_f32 v[14:15], v[14:15], v[128:129] op_sel:[0,1]
	v_pk_mul_f32 v[4:5], v[4:5], v[130:131] op_sel_hi:[1,0]
	v_pk_mul_f32 v[2:3], v[2:3], v[130:131] op_sel_hi:[1,0]
	v_pk_mul_f32 v[8:9], v[8:9], v[130:131] op_sel:[0,1]
	v_pk_mul_f32 v[6:7], v[6:7], v[130:131] op_sel:[0,1]

;     ...
;     const float* src = W + (size_t)(k0 + 2 * q) * N + n0 + 4 * r16;
;     f32x4 v[16];
; #pragma unroll
;     for (int j = 0; j < 16; ++j) v[j] = *(const f32x4*)(src + (size_t)(8 * (j >> 1) + (j & 1)) * N);
;     if (nscale) { const f32x4 ns = *(const f32x4*)(nscale + n0 + 4 * r16);
; #pragma unroll
;         for (int j = 0; j < 16; ++j) v[j] = v[j] * ns; }
;     if (kscale) {
; #pragma unroll
;         for (int i = 0; i < 8; ++i) { const f32x2 g = *(const f32x2*)(kscale + k0 + 8 * i + 2 * q); v[2 * i] = v[2 * i] * g[0]; v[2 * i + 1] = v[2 * i + 1] * g[1]; } }
; __device__ __forceinline__ void weights_pass(const Args& a, LAS unsigned char* scr, int gw, int NGW, int lane, int pass) {
;     ...
;         if (r < I_QM) { transpose_item<1>(a.in[I_WKM] + (size_t)l * DM * MW, DM, MW, (bf16_t*)(ws + WS_WKV) + (size_t)l * 1024 * DM, a.in[I_GMEM] + l * DM, nullptr, 0, scr, r, lane); continue; } r -= I_QM;
.LBB0_20:
	s_and_b64 vcc, exec, s[14:15]
	s_cbranch_vccz .LBB0_38
	v_readlane_b32 s60, v250, 46
	v_readlane_b32 s66, v250, 52
	v_readlane_b32 s67, v250, 53
	s_add_u32 s56, s66, s12
	s_mul_i32 s8, s10, 0xfffaa800
	s_addc_u32 s57, s67, s13
	s_add_i32 s8, s31, s8
	s_addk_i32 s8, 0xf000
	s_and_b32 s14, s8, 0x7ffc0
	v_or_b32_e32 v2, s14, v74
	v_lshlrev_b32_e32 v2, 11, v2
	v_mov_b32_e32 v3, v71
	v_lshl_add_u64 v[2:3], s[56:57], 0, v[2:3]
	s_lshl_b32 s8, s54, 2
	v_lshl_add_u64 v[2:3], v[2:3], 0, s[8:9]
	v_lshl_add_u64 v[2:3], v[2:3], 0, v[70:71]
	v_add_co_u32_e32 v4, vcc, s39, v2
	global_load_dwordx4 v[58:61], v[2:3], off nt
	global_load_dwordx4 v[62:65], v[2:3], off offset:2048 nt
	v_addc_co_u32_e32 v5, vcc, 0, v3, vcc
	global_load_dwordx4 v[50:53], v[4:5], off nt
	global_load_dwordx4 v[54:57], v[4:5], off offset:2048 nt
	v_add_co_u32_e32 v4, vcc, s40, v2
	v_readlane_b32 s62, v250, 48
	s_nop 0
	v_addc_co_u32_e32 v5, vcc, 0, v3, vcc
	global_load_dwordx4 v[42:45], v[4:5], off nt
	global_load_dwordx4 v[46:49], v[4:5], off offset:2048 nt
	v_add_co_u32_e32 v4, vcc, s41, v2
	v_readlane_b32 s63, v250, 49
	s_nop 0
	v_addc_co_u32_e32 v5, vcc, 0, v3, vcc
	global_load_dwordx4 v[34:37], v[4:5], off nt
	global_load_dwordx4 v[38:41], v[4:5], off offset:2048 nt
	v_add_co_u32_e32 v4, vcc, s42, v2
	v_readlane_b32 s61, v250, 47
	s_nop 0
	v_addc_co_u32_e32 v5, vcc, 0, v3, vcc
	global_load_dwordx4 v[26:29], v[4:5], off nt
	global_load_dwordx4 v[30:33], v[4:5], off offset:2048 nt
	v_add_co_u32_e32 v4, vcc, s43, v2
	v_readlane_b32 s64, v250, 50
	s_nop 0
	v_addc_co_u32_e32 v5, vcc, 0, v3, vcc
	global_load_dwordx4 v[18:21], v[4:5], off nt
	global_load_dwordx4 v[22:25], v[4:5], off offset:2048 nt
	v_add_co_u32_e32 v4, vcc, 0x18000, v2
	v_readlane_b32 s65, v250, 51
	s_nop 0
	v_addc_co_u32_e32 v5, vcc, 0, v3, vcc
	v_add_co_u32_e32 v6, vcc, 0x1c000, v2
	global_load_dwordx4 v[10:13], v[4:5], off nt
	global_load_dwordx4 v[14:17], v[4:5], off offset:2048 nt
	v_addc_co_u32_e32 v7, vcc, 0, v3, vcc
	global_load_dwordx4 v[2:5], v[6:7], off nt
	s_nop 0
	global_load_dwordx4 v[6:9], v[6:7], off offset:2048 nt
	s_and_b64 vcc, exec, s[0:1]
	v_readlane_b32 s68, v250, 54
	v_readlane_b32 s69, v250, 55
	v_readlane_b32 s70, v250, 56
	v_readlane_b32 s71, v250, 57
	v_readlane_b32 s72, v250, 58
	v_readlane_b32 s73, v250, 59
	v_readlane_b32 s74, v250, 60
	v_readlane_b32 s75, v250, 61
	s_cbranch_vccnz .LBB0_23
	s_lshl_b32 s0, s10, 12
	s_ashr_i32 s1, s0, 31
	s_lshl_b64 s[0:1], s[0:1], 2
	s_add_u32 s0, s62, s0
	s_addc_u32 s1, s63, s1
	s_lshl_b32 s8, s14, 2
	s_add_u32 s0, s0, s8
	s_addc_u32 s1, s1, 0
	global_load_dwordx2 v[116:117], v107, s[0:1]
	global_load_dwordx2 v[118:119], v107, s[0:1] offset:32
	global_load_dwordx2 v[120:121], v107, s[0:1] offset:64
	global_load_dwordx2 v[122:123], v107, s[0:1] offset:96
	global_load_dwordx2 v[124:125], v107, s[0:1] offset:128
	global_load_dwordx2 v[126:127], v107, s[0:1] offset:160
	global_load_dwordx2 v[128:129], v107, s[0:1] offset:192
	global_load_dwordx2 v[130:131], v107, s[0:1] offset:224
	s_waitcnt vmcnt(0)
	v_pk_mul_f32 v[60:61], v[60:61], v[116:117] op_sel_hi:[1,0]
	v_pk_mul_f32 v[58:59], v[58:59], v[116:117] op_sel_hi:[1,0]
	v_pk_mul_f32 v[64:65], v[64:65], v[116:117] op_sel:[0,1]
	v_pk_mul_f32 v[62:63], v[62:63], v[116:117] op_sel:[0,1]
	v_pk_mul_f32 v[52:53], v[52:53], v[118:119] op_sel_hi:[1,0]
	v_pk_mul_f32 v[50:51], v[50:51], v[118:119] op_sel_hi:[1,0]
	v_pk_mul_f32 v[56:57], v[56:57], v[118:119] op_sel:[0,1]
	v_pk_mul_f32 v[54:55], v[54:55], v[118:119] op_sel:[0,1]
	v_pk_mul_f32 v[44:45], v[44:45], v[120:121] op_sel_hi:[1,0]
	v_pk_mul_f32 v[42:43], v[42:43], v[120:121] op_sel_hi:[1,0]
	v_pk_mul_f32 v[48:49], v[48:49], v[120:121] op_sel:[0,1]
	v_pk_mul_f32 v[46:47], v[46:47], v[120:121] op_sel:[0,1]
	v_pk_mul_f32 v[36:37], v[36:37], v[122:123] op_sel_hi:[1,0]
	v_pk_mul_f32 v[34:35], v[34:35], v[122:123] op_sel_hi:[1,0]
	v_pk_mul_f32 v[40:41], v[40:41], v[122:123] op_sel:[0,1]
	v_pk_mul_f32 v[38:39], v[38:39], v[122:123] op_sel:[0,1]
	v_pk_mul_f32 v[28:29], v[28:29], v[124:125] op_sel_hi:[1,0]
	v_pk_mul_f32 v[26:27], v[26:27], v[124:125] op_sel_hi:[1,0]
	v_pk_mul_f32 v[32:33], v[32:33], v[124:125] op_sel:[0,1]
	v_pk_mul_f32 v[30:31], v[30:31], v[124:125] op_sel:[0,1]
	v_pk_mul_f32 v[20:21], v[20:21], v[126:127] op_sel_hi:[1,0]
	v_pk_mul_f32 v[18:19], v[18:19], v[126:127] op_sel_hi:[1,0]
	v_pk_mul_f32 v[24:25], v[24:25], v[126:127] op_sel:[0,1]
	v_pk_mul_f32 v[22:23], v[22:23], v[126:127] op_sel:[0,1]
	v_pk_mul_f32 v[12:13], v[12:13], v[128:129] op_sel_hi:[1,0]
	v_pk_mul_f32 v[10:11], v[10:11], v[128:129] op_sel_hi:[1,0]
	v_pk_mul_f32 v[16:17], v[16:17], v[128:129] op_sel:[0,1]
	v_pk_mul_f32 v[14:15], v[14:15], v[128:129] op_sel:[0,1]
	v_pk_mul_f32 v[4:5], v[4:5], v[130:131] op_sel_hi:[1,0]
	v_pk_mul_f32 v[2:3], v[2:3], v[130:131] op_sel_hi:[1,0]
	v_pk_mul_f32 v[8:9], v[8:9], v[130:131] op_sel:[0,1]
	v_pk_mul_f32 v[6:7], v[6:7], v[130:131] op_sel:[0,1]

;     ...
;     const float* src = W + (size_t)(k0 + 2 * q) * N + n0 + 4 * r16;
;     f32x4 v[16];
; #pragma unroll
;     for (int j = 0; j < 16; ++j) v[j] = *(const f32x4*)(src + (size_t)(8 * (j >> 1) + (j & 1)) * N);
;     if (nscale) { const f32x4 ns = *(const f32x4*)(nscale + n0 + 4 * r16);
; #pragma unroll
;         for (int j = 0; j < 16; ++j) v[j] = v[j] * ns; }
;     if (kscale) {
; #pragma unroll
;         for (int i = 0; i < 8; ++i) { const f32x2 g = *(const f32x2*)(kscale + k0 + 8 * i + 2 * q); v[2 * i] = v[2 * i] * g[0]; v[2 * i + 1] = v[2 * i + 1] * g[1]; } }
; __device__ __forceinline__ void weights_pass(const Args& a, LAS unsigned char* scr, int gw, int NGW, int lane, int pass) {
;     ...
;         if (r < I_QM) { transpose_item<0>(a.in[I_WQM] + (size_t)l * DM * MW, DM, MW, (bf16_t*)(wl + WL_Q), a.in[I_GCROSS] + l * DM, nullptr, 0, scr, r, lane); continue; } r -= I_QM;
.LBB0_25:
	v_readlane_b32 s52, v250, 46
	v_readlane_b32 s56, v250, 50
	v_readlane_b32 s57, v250, 51
	s_add_u32 s0, s56, s12
	s_mul_i32 s2, s10, 0xfffaa800
	s_addc_u32 s1, s57, s13
	s_add_i32 s2, s31, s2
	s_and_b32 s2, s2, 0x7ffc0
	s_lshl_b32 s8, s49, 6
	v_or_b32_e32 v2, s2, v74
	s_and_b32 s12, s8, 0x1c0
	v_lshlrev_b32_e32 v2, 11, v2
	v_mov_b32_e32 v3, v71
	v_lshl_add_u64 v[2:3], s[0:1], 0, v[2:3]
	s_lshl_b32 s8, s12, 2
	v_lshl_add_u64 v[2:3], v[2:3], 0, s[8:9]
	v_lshl_add_u64 v[2:3], v[2:3], 0, v[70:71]
	v_add_co_u32_e32 v4, vcc, s39, v2
	global_load_dwordx4 v[58:61], v[2:3], off nt
	global_load_dwordx4 v[62:65], v[2:3], off offset:2048 nt
	v_addc_co_u32_e32 v5, vcc, 0, v3, vcc
	global_load_dwordx4 v[50:53], v[4:5], off nt
	global_load_dwordx4 v[54:57], v[4:5], off offset:2048 nt
	v_add_co_u32_e32 v4, vcc, s40, v2
	v_readlane_b32 s53, v250, 47
	s_nop 0
	v_addc_co_u32_e32 v5, vcc, 0, v3, vcc
	global_load_dwordx4 v[42:45], v[4:5], off nt
	global_load_dwordx4 v[46:49], v[4:5], off offset:2048 nt
	v_add_co_u32_e32 v4, vcc, s41, v2
	v_readlane_b32 s54, v250, 48
	s_nop 0
	v_addc_co_u32_e32 v5, vcc, 0, v3, vcc
	global_load_dwordx4 v[34:37], v[4:5], off nt
	global_load_dwordx4 v[38:41], v[4:5], off offset:2048 nt
	v_add_co_u32_e32 v4, vcc, s42, v2
	v_readlane_b32 s55, v250, 49
	s_nop 0
	v_addc_co_u32_e32 v5, vcc, 0, v3, vcc
	global_load_dwordx4 v[26:29], v[4:5], off nt
	global_load_dwordx4 v[30:33], v[4:5], off offset:2048 nt
	v_add_co_u32_e32 v4, vcc, s43, v2
	v_readlane_b32 s58, v250, 52
	s_nop 0
	v_addc_co_u32_e32 v5, vcc, 0, v3, vcc
	global_load_dwordx4 v[18:21], v[4:5], off nt
	global_load_dwordx4 v[22:25], v[4:5], off offset:2048 nt
	v_add_co_u32_e32 v4, vcc, 0x18000, v2
	v_readlane_b32 s59, v250, 53
	s_nop 0
	v_addc_co_u32_e32 v5, vcc, 0, v3, vcc
	v_add_co_u32_e32 v6, vcc, 0x1c000, v2
	global_load_dwordx4 v[10:13], v[4:5], off nt
	global_load_dwordx4 v[14:17], v[4:5], off offset:2048 nt
	v_addc_co_u32_e32 v7, vcc, 0, v3, vcc
	global_load_dwordx4 v[2:5], v[6:7], off nt
	s_nop 0
	global_load_dwordx4 v[6:9], v[6:7], off offset:2048 nt
	s_andn2_b64 vcc, exec, s[4:5]
	v_readlane_b32 s60, v250, 54
	v_readlane_b32 s61, v250, 55
	v_readlane_b32 s62, v250, 56
	v_readlane_b32 s63, v250, 57
	v_readlane_b32 s64, v250, 58
	v_readlane_b32 s65, v250, 59
	v_readlane_b32 s66, v250, 60
	v_readlane_b32 s67, v250, 61
	s_cbranch_vccnz .LBB0_27
	s_lshl_b32 s0, s10, 12
	s_ashr_i32 s1, s0, 31
	s_lshl_b64 s[0:1], s[0:1], 2
	s_add_u32 s0, s52, s0
	s_addc_u32 s1, s53, s1
	s_lshl_b32 s8, s2, 2
	s_add_u32 s0, s0, s8
	s_addc_u32 s1, s1, 0
	global_load_dwordx2 v[116:117], v107, s[0:1]
	global_load_dwordx2 v[118:119], v107, s[0:1] offset:32
	global_load_dwordx2 v[120:121], v107, s[0:1] offset:64
	global_load_dwordx2 v[122:123], v107, s[0:1] offset:96
	global_load_dwordx2 v[124:125], v107, s[0:1] offset:128
	global_load_dwordx2 v[126:127], v107, s[0:1] offset:160
	global_load_dwordx2 v[128:129], v107, s[0:1] offset:192
	global_load_dwordx2 v[130:131], v107, s[0:1] offset:224
	s_waitcnt vmcnt(0)
	v_pk_mul_f32 v[60:61], v[60:61], v[116:117] op_sel_hi:[1,0]
	v_pk_mul_f32 v[58:59], v[58:59], v[116:117] op_sel_hi:[1,0]
	v_pk_mul_f32 v[64:65], v[64:65], v[116:117] op_sel:[0,1]
	v_pk_mul_f32 v[62:63], v[62:63], v[116:117] op_sel:[0,1]
	v_pk_mul_f32 v[52:53], v[52:53], v[118:119] op_sel_hi:[1,0]
	v_pk_mul_f32 v[50:51], v[50:51], v[118:119] op_sel_hi:[1,0]
	v_pk_mul_f32 v[56:57], v[56:57], v[118:119] op_sel:[0,1]
	v_pk_mul_f32 v[54:55], v[54:55], v[118:119] op_sel:[0,1]
	v_pk_mul_f32 v[44:45], v[44:45], v[120:121] op_sel_hi:[1,0]
	v_pk_mul_f32 v[42:43], v[42:43], v[120:121] op_sel_hi:[1,0]
	v_pk_mul_f32 v[48:49], v[48:49], v[120:121] op_sel:[0,1]
	v_pk_mul_f32 v[46:47], v[46:47], v[120:121] op_sel:[0,1]
	v_pk_mul_f32 v[36:37], v[36:37], v[122:123] op_sel_hi:[1,0]
	v_pk_mul_f32 v[34:35], v[34:35], v[122:123] op_sel_hi:[1,0]
	v_pk_mul_f32 v[40:41], v[40:41], v[122:123] op_sel:[0,1]
	v_pk_mul_f32 v[38:39], v[38:39], v[122:123] op_sel:[0,1]
	v_pk_mul_f32 v[28:29], v[28:29], v[124:125] op_sel_hi:[1,0]
	v_pk_mul_f32 v[26:27], v[26:27], v[124:125] op_sel_hi:[1,0]
	v_pk_mul_f32 v[32:33], v[32:33], v[124:125] op_sel:[0,1]
	v_pk_mul_f32 v[30:31], v[30:31], v[124:125] op_sel:[0,1]
	v_pk_mul_f32 v[20:21], v[20:21], v[126:127] op_sel_hi:[1,0]
	v_pk_mul_f32 v[18:19], v[18:19], v[126:127] op_sel_hi:[1,0]
	v_pk_mul_f32 v[24:25], v[24:25], v[126:127] op_sel:[0,1]
	v_pk_mul_f32 v[22:23], v[22:23], v[126:127] op_sel:[0,1]
	v_pk_mul_f32 v[12:13], v[12:13], v[128:129] op_sel_hi:[1,0]
	v_pk_mul_f32 v[10:11], v[10:11], v[128:129] op_sel_hi:[1,0]
	v_pk_mul_f32 v[16:17], v[16:17], v[128:129] op_sel:[0,1]
	v_pk_mul_f32 v[14:15], v[14:15], v[128:129] op_sel:[0,1]
	v_pk_mul_f32 v[4:5], v[4:5], v[130:131] op_sel_hi:[1,0]
	v_pk_mul_f32 v[2:3], v[2:3], v[130:131] op_sel_hi:[1,0]
	v_pk_mul_f32 v[8:9], v[8:9], v[130:131] op_sel:[0,1]
	v_pk_mul_f32 v[6:7], v[6:7], v[130:131] op_sel:[0,1]

;     ...
;     const float* src = W + (size_t)(k0 + 2 * q) * N + n0 + 4 * r16;
;     f32x4 v[16];
; #pragma unroll
;     for (int j = 0; j < 16; ++j) v[j] = *(const f32x4*)(src + (size_t)(8 * (j >> 1) + (j & 1)) * N);
;     if (nscale) { const f32x4 ns = *(const f32x4*)(nscale + n0 + 4 * r16);
; #pragma unroll
;         for (int j = 0; j < 16; ++j) v[j] = v[j] * ns; }
;     if (kscale) {
; #pragma unroll
;         for (int i = 0; i < 8; ++i) { const f32x2 g = *(const f32x2*)(kscale + k0 + 8 * i + 2 * q); v[2 * i] = v[2 * i] * g[0]; v[2 * i + 1] = v[2 * i + 1] * g[1]; } }
; __device__ __forceinline__ void weights_pass(const Args& a, LAS unsigned char* scr, int gw, int NGW, int lane, int pass) {
;     ...
;         if (r < I_IN) { transpose_item<1>(a.in[I_WIN] + (size_t)l * DM * INW, DM, INW, (bf16_t*)(wl + WL_IN), a.in[I_GMIX] + l * DM, nullptr, 0, scr, r, lane); continue; } r -= I_IN;
.LBB0_35:
	s_andn2_b64 vcc, exec, s[12:13]
	s_cbranch_vccnz .LBB0_10
	v_readlane_b32 s52, v250, 10
	s_mul_i32 s2, s10, 0x4800000
	v_readlane_b32 s54, v250, 12
	s_mul_hi_i32 s1, s10, 0x4800000
	v_readlane_b32 s55, v250, 13
	s_add_u32 s14, s54, s2
	s_addc_u32 s15, s55, s1
	s_mul_hi_i32 s1, s49, 0x38e38e39
	s_lshr_b32 s2, s1, 31
	s_ashr_i32 s1, s1, 4
	s_add_i32 s1, s1, s2
	s_mul_i32 s0, s10, 0xab00
	s_mul_i32 s2, s1, 0xffffffb8
	s_lshl_b32 s12, s1, 6
	s_sub_i32 s0, s2, s0
	v_or_b32_e32 v2, s12, v74
	s_movk_i32 s1, 0x1200
	s_add_i32 s0, s46, s0
	v_mul_lo_u32 v2, v2, s1
	s_lshl_b32 s0, s0, 6
	v_ashrrev_i32_e32 v3, 31, v2
	v_lshl_add_u64 v[2:3], v[2:3], 2, s[14:15]
	s_ashr_i32 s1, s0, 31
	v_lshl_add_u64 v[2:3], s[0:1], 2, v[2:3]
	v_lshl_add_u64 v[2:3], v[2:3], 0, v[70:71]
	v_add_co_u32_e32 v4, vcc, s39, v2
	s_mov_b32 s1, 0x28000
	s_nop 0
	v_addc_co_u32_e32 v5, vcc, 0, v3, vcc
	global_load_dwordx4 v[58:61], v[2:3], off nt
	global_load_dwordx4 v[62:65], v[4:5], off offset:2048 nt
	v_add_co_u32_e32 v4, vcc, s45, v2
	v_readlane_b32 s53, v250, 11
	s_nop 0
	v_addc_co_u32_e32 v5, vcc, 0, v3, vcc
	v_add_co_u32_e32 v6, vcc, s1, v2
	s_mov_b32 s1, 0x48000
	s_nop 0
	v_addc_co_u32_e32 v7, vcc, 0, v3, vcc
	global_load_dwordx4 v[50:53], v[4:5], off nt
	global_load_dwordx4 v[54:57], v[6:7], off offset:2048 nt
	v_add_co_u32_e32 v4, vcc, s1, v2
	s_mov_b32 s1, 0x4c000
	s_nop 0
	v_addc_co_u32_e32 v5, vcc, 0, v3, vcc
	v_add_co_u32_e32 v6, vcc, s1, v2
	s_mov_b32 s1, 0x6c000
	s_nop 0
	v_addc_co_u32_e32 v7, vcc, 0, v3, vcc
	global_load_dwordx4 v[42:45], v[4:5], off nt
	global_load_dwordx4 v[46:49], v[6:7], off offset:2048 nt
	v_add_co_u32_e32 v4, vcc, s1, v2
	s_mov_b32 s1, 0x70000
	s_nop 0
	v_addc_co_u32_e32 v5, vcc, 0, v3, vcc
	v_add_co_u32_e32 v6, vcc, s1, v2
	s_mov_b32 s1, 0x90000
	s_nop 0
	v_addc_co_u32_e32 v7, vcc, 0, v3, vcc
	global_load_dwordx4 v[26:29], v[4:5], off nt
	global_load_dwordx4 v[38:41], v[6:7], off offset:2048 nt
	v_add_co_u32_e32 v4, vcc, s1, v2
	s_mov_b32 s1, 0x94000
	s_nop 0
	v_addc_co_u32_e32 v5, vcc, 0, v3, vcc
	v_add_co_u32_e32 v6, vcc, s1, v2
	s_mov_b32 s1, 0xb4000
	s_nop 0
	v_addc_co_u32_e32 v7, vcc, 0, v3, vcc
	global_load_dwordx4 v[18:21], v[4:5], off nt
	global_load_dwordx4 v[34:37], v[6:7], off offset:2048 nt
	v_add_co_u32_e32 v4, vcc, s1, v2
	s_mov_b32 s1, 0xb8000
	s_nop 0
	v_addc_co_u32_e32 v5, vcc, 0, v3, vcc
	v_add_co_u32_e32 v6, vcc, s1, v2
	s_ashr_i32 s13, s12, 31
	s_nop 0
	v_addc_co_u32_e32 v7, vcc, 0, v3, vcc
	global_load_dwordx4 v[14:17], v[4:5], off nt
	global_load_dwordx4 v[30:33], v[6:7], off offset:2048 nt
	v_add_co_u32_e32 v4, vcc, 0xd8000, v2
	v_readlane_b32 s56, v250, 14
	s_nop 0
	v_addc_co_u32_e32 v5, vcc, 0, v3, vcc
	v_add_co_u32_e32 v10, vcc, 0xdc000, v2
	v_readlane_b32 s57, v250, 15
	s_nop 0
	v_addc_co_u32_e32 v11, vcc, 0, v3, vcc
	global_load_dwordx4 v[6:9], v[4:5], off nt
	global_load_dwordx4 v[22:25], v[10:11], off offset:2048 nt
	v_add_co_u32_e32 v4, vcc, 0xfc000, v2
	v_readlane_b32 s58, v250, 16
	s_nop 0
	v_addc_co_u32_e32 v5, vcc, 0, v3, vcc
	v_add_co_u32_e32 v10, vcc, 0x100000, v2
	v_readlane_b32 s59, v250, 17
	s_nop 0
	v_addc_co_u32_e32 v11, vcc, 0, v3, vcc
	global_load_dwordx4 v[2:5], v[4:5], off nt
	s_nop 0
	global_load_dwordx4 v[10:13], v[10:11], off offset:2048 nt
	s_andn2_b64 vcc, exec, s[6:7]
	v_readlane_b32 s60, v250, 18
	v_readlane_b32 s61, v250, 19
	v_readlane_b32 s62, v250, 20
	v_readlane_b32 s63, v250, 21
	v_readlane_b32 s64, v250, 22
	v_readlane_b32 s65, v250, 23
	v_readlane_b32 s66, v250, 24
	v_readlane_b32 s67, v250, 25
	s_cbranch_vccnz .LBB0_9
	s_lshl_b32 s10, s10, 12
	s_ashr_i32 s11, s10, 31
	s_lshl_b64 s[10:11], s[10:11], 2
	s_add_u32 s1, s52, s10
	s_addc_u32 s2, s53, s11
	s_lshl_b64 s[10:11], s[12:13], 2
	s_add_u32 s10, s1, s10
	s_addc_u32 s11, s2, s11
	global_load_dwordx2 v[116:117], v107, s[10:11]
	global_load_dwordx2 v[118:119], v107, s[10:11] offset:32
	global_load_dwordx2 v[120:121], v107, s[10:11] offset:64
	global_load_dwordx2 v[122:123], v107, s[10:11] offset:96
	global_load_dwordx2 v[124:125], v107, s[10:11] offset:128
	global_load_dwordx2 v[126:127], v107, s[10:11] offset:160
	global_load_dwordx2 v[128:129], v107, s[10:11] offset:192
	global_load_dwordx2 v[130:131], v107, s[10:11] offset:224
	s_waitcnt vmcnt(0)
	v_pk_mul_f32 v[60:61], v[60:61], v[116:117] op_sel_hi:[1,0]
	v_pk_mul_f32 v[58:59], v[58:59], v[116:117] op_sel_hi:[1,0]
	v_pk_mul_f32 v[64:65], v[64:65], v[116:117] op_sel:[0,1]
	v_pk_mul_f32 v[62:63], v[62:63], v[116:117] op_sel:[0,1]
	v_pk_mul_f32 v[52:53], v[52:53], v[118:119] op_sel_hi:[1,0]
	v_pk_mul_f32 v[50:51], v[50:51], v[118:119] op_sel_hi:[1,0]
	v_pk_mul_f32 v[56:57], v[56:57], v[118:119] op_sel:[0,1]
	v_pk_mul_f32 v[54:55], v[54:55], v[118:119] op_sel:[0,1]
	v_pk_mul_f32 v[44:45], v[44:45], v[120:121] op_sel_hi:[1,0]
	v_pk_mul_f32 v[42:43], v[42:43], v[120:121] op_sel_hi:[1,0]
	v_pk_mul_f32 v[48:49], v[48:49], v[120:121] op_sel:[0,1]
	v_pk_mul_f32 v[46:47], v[46:47], v[120:121] op_sel:[0,1]
	v_pk_mul_f32 v[28:29], v[28:29], v[122:123] op_sel_hi:[1,0]
	v_pk_mul_f32 v[26:27], v[26:27], v[122:123] op_sel_hi:[1,0]
	v_pk_mul_f32 v[40:41], v[40:41], v[122:123] op_sel:[0,1]
	v_pk_mul_f32 v[38:39], v[38:39], v[122:123] op_sel:[0,1]
	v_pk_mul_f32 v[20:21], v[20:21], v[124:125] op_sel_hi:[1,0]
	v_pk_mul_f32 v[18:19], v[18:19], v[124:125] op_sel_hi:[1,0]
	v_pk_mul_f32 v[36:37], v[36:37], v[124:125] op_sel:[0,1]
	v_pk_mul_f32 v[34:35], v[34:35], v[124:125] op_sel:[0,1]
	v_pk_mul_f32 v[16:17], v[16:17], v[126:127] op_sel_hi:[1,0]
	v_pk_mul_f32 v[14:15], v[14:15], v[126:127] op_sel_hi:[1,0]
	v_pk_mul_f32 v[32:33], v[32:33], v[126:127] op_sel:[0,1]
	v_pk_mul_f32 v[30:31], v[30:31], v[126:127] op_sel:[0,1]
	v_pk_mul_f32 v[8:9], v[8:9], v[128:129] op_sel_hi:[1,0]
	v_pk_mul_f32 v[6:7], v[6:7], v[128:129] op_sel_hi:[1,0]
	v_pk_mul_f32 v[24:25], v[24:25], v[128:129] op_sel:[0,1]
	v_pk_mul_f32 v[22:23], v[22:23], v[128:129] op_sel:[0,1]
	v_pk_mul_f32 v[4:5], v[4:5], v[130:131] op_sel_hi:[1,0]
	v_pk_mul_f32 v[2:3], v[2:3], v[130:131] op_sel_hi:[1,0]
	v_pk_mul_f32 v[12:13], v[12:13], v[130:131] op_sel:[0,1]
	v_pk_mul_f32 v[10:11], v[10:11], v[130:131] op_sel:[0,1]
	s_branch .LBB0_9

;     ...
;     const float* src = W + (size_t)(k0 + 2 * q) * N + n0 + 4 * r16;
;     f32x4 v[16];
; #pragma unroll
;     for (int j = 0; j < 16; ++j) v[j] = *(const f32x4*)(src + (size_t)(8 * (j >> 1) + (j & 1)) * N);
;     if (nscale) { const f32x4 ns = *(const f32x4*)(nscale + n0 + 4 * r16);
; #pragma unroll
;         for (int j = 0; j < 16; ++j) v[j] = v[j] * ns; }
;     if (kscale) {
; #pragma unroll
;         for (int i = 0; i < 8; ++i) { const f32x2 g = *(const f32x2*)(kscale + k0 + 8 * i + 2 * q); v[2 * i] = v[2 * i] * g[0]; v[2 * i + 1] = v[2 * i + 1] * g[1]; } }
; __device__ __forceinline__ void weights_pass(const Args& a, LAS unsigned char* scr, int gw, int NGW, int lane, int pass) {
;     ...
;         if (r < I_G) { transpose_item<3>(a.in[I_WUP] + (size_t)l * DM * DFF, DM, DFF, (bf16_t*)(wl + WL_GU), a.in[I_GFFN] + l * DM, nullptr, 0, scr, r, lane); continue; } r -= I_G;
.LBB0_635:
	s_andn2_b64 vcc, exec, s[4:5]
	s_cbranch_vccnz .LBB0_639
	v_readlane_b32 s36, v250, 0
	v_readlane_b32 s40, v250, 4
	v_readlane_b32 s41, v250, 5
	s_add_u32 s4, s40, s3
	s_addc_u32 s5, s41, s2
	s_add_i32 s6, s20, 0xab00
	s_and_b32 s7, s6, 0xffff
	s_mul_i32 s7, s7, 0xbe83
	s_lshr_b32 s14, s7, 23
	s_mul_i32 s7, s14, 0xac
	s_sub_i32 s6, s6, s7
	s_and_b32 s7, s6, 0xffff
	s_lshl_b32 s6, s14, 6
	v_or_b32_e32 v4, s6, v72
	v_mul_u32_u24_e32 v4, 0x2b00, v4
	v_lshlrev_b32_e32 v4, 2, v4
	v_mov_b32_e32 v5, v2
	v_lshl_add_u64 v[4:5], s[4:5], 0, v[4:5]
	s_lshl_b32 s14, s7, 8
	v_lshl_add_u64 v[4:5], v[4:5], 0, s[14:15]
	v_lshlrev_b32_e32 v6, 2, v68
	v_mov_b32_e32 v7, v2
	v_lshl_add_u64 v[4:5], v[4:5], 0, v[6:7]
	s_mov_b32 s4, 0xa000
	v_add_co_u32_e32 v6, vcc, s4, v4
	s_mov_b32 s4, 0x56000
	s_nop 0
	v_addc_co_u32_e32 v7, vcc, 0, v5, vcc
	global_load_dwordx4 v[60:63], v[4:5], off nt
	global_load_dwordx4 v[64:67], v[6:7], off offset:3072 nt
	v_add_co_u32_e32 v6, vcc, s4, v4
	s_mov_b32 s4, 0x60000
	s_nop 0
	v_addc_co_u32_e32 v7, vcc, 0, v5, vcc
	v_add_co_u32_e32 v8, vcc, s4, v4
	s_mov_b32 s4, 0xac000
	s_nop 0
	v_addc_co_u32_e32 v9, vcc, 0, v5, vcc
	global_load_dwordx4 v[52:55], v[6:7], off nt
	global_load_dwordx4 v[56:59], v[8:9], off offset:3072 nt
	v_add_co_u32_e32 v6, vcc, s4, v4
	s_mov_b32 s4, 0xb6000
	s_nop 0
	v_addc_co_u32_e32 v7, vcc, 0, v5, vcc
	v_add_co_u32_e32 v8, vcc, s4, v4
	s_mov_b32 s4, 0x102000
	s_nop 0
	v_addc_co_u32_e32 v9, vcc, 0, v5, vcc
	global_load_dwordx4 v[44:47], v[6:7], off nt
	global_load_dwordx4 v[48:51], v[8:9], off offset:3072 nt
	v_add_co_u32_e32 v6, vcc, s4, v4
	s_mov_b32 s4, 0x10c000
	s_nop 0
	v_addc_co_u32_e32 v7, vcc, 0, v5, vcc
	v_add_co_u32_e32 v8, vcc, s4, v4
	s_mov_b32 s4, 0x158000
	s_nop 0
	v_addc_co_u32_e32 v9, vcc, 0, v5, vcc
	global_load_dwordx4 v[36:39], v[6:7], off nt
	global_load_dwordx4 v[40:43], v[8:9], off offset:3072 nt
	v_add_co_u32_e32 v6, vcc, s4, v4
	s_mov_b32 s4, 0x162000
	s_nop 0
	v_addc_co_u32_e32 v7, vcc, 0, v5, vcc
	v_add_co_u32_e32 v8, vcc, s4, v4
	s_mov_b32 s4, 0x1ae000
	s_nop 0
	v_addc_co_u32_e32 v9, vcc, 0, v5, vcc
	global_load_dwordx4 v[20:23], v[6:7], off nt
	global_load_dwordx4 v[32:35], v[8:9], off offset:3072 nt
	v_add_co_u32_e32 v6, vcc, s4, v4
	s_mov_b32 s4, 0x1b8000
	s_nop 0
	v_addc_co_u32_e32 v7, vcc, 0, v5, vcc
	v_add_co_u32_e32 v8, vcc, s4, v4
	s_mov_b32 s4, 0x204000
	s_nop 0
	v_addc_co_u32_e32 v9, vcc, 0, v5, vcc
	global_load_dwordx4 v[16:19], v[6:7], off nt
	global_load_dwordx4 v[28:31], v[8:9], off offset:3072 nt
	v_add_co_u32_e32 v6, vcc, s4, v4
	v_readlane_b32 s4, v253, 7
	s_nop 0
	v_addc_co_u32_e32 v7, vcc, 0, v5, vcc
	v_add_co_u32_e32 v12, vcc, 0x20e000, v4
	v_readlane_b32 s5, v253, 8
	s_nop 0
	v_addc_co_u32_e32 v13, vcc, 0, v5, vcc
	global_load_dwordx4 v[8:11], v[6:7], off nt
	global_load_dwordx4 v[24:27], v[12:13], off offset:3072 nt
	v_add_co_u32_e32 v6, vcc, 0x25a000, v4
	v_readlane_b32 s37, v250, 1
	s_nop 0
	v_addc_co_u32_e32 v7, vcc, 0, v5, vcc
	v_add_co_u32_e32 v12, vcc, 0x264000, v4
	v_readlane_b32 s38, v250, 2
	s_nop 0
	v_addc_co_u32_e32 v13, vcc, 0, v5, vcc
	global_load_dwordx4 v[4:7], v[6:7], off nt
	s_nop 0
	global_load_dwordx4 v[12:15], v[12:13], off offset:3072 nt
	s_andn2_b64 vcc, exec, s[4:5]
	v_readlane_b32 s39, v250, 3
	v_readlane_b32 s42, v250, 6
	v_readlane_b32 s43, v250, 7
	s_cbranch_vccnz .LBB0_638
	s_lshl_b32 s4, s0, 12
	s_ashr_i32 s5, s4, 31
	s_lshl_b64 s[4:5], s[4:5], 2
	s_add_u32 s4, s36, s4
	s_addc_u32 s5, s37, s5
	s_lshl_b32 s14, s6, 2
	s_add_u32 s4, s4, s14
	s_addc_u32 s5, s5, 0
	v_lshlrev_b32_e32 v106, 2, v72
	global_load_dwordx2 v[116:117], v106, s[4:5]
	global_load_dwordx2 v[118:119], v106, s[4:5] offset:32
	global_load_dwordx2 v[120:121], v106, s[4:5] offset:64
	global_load_dwordx2 v[122:123], v106, s[4:5] offset:96
	global_load_dwordx2 v[124:125], v106, s[4:5] offset:128
	global_load_dwordx2 v[126:127], v106, s[4:5] offset:160
	global_load_dwordx2 v[128:129], v106, s[4:5] offset:192
	global_load_dwordx2 v[130:131], v106, s[4:5] offset:224
	s_waitcnt vmcnt(0)
	v_pk_mul_f32 v[62:63], v[62:63], v[116:117] op_sel_hi:[1,0]
	v_pk_mul_f32 v[60:61], v[60:61], v[116:117] op_sel_hi:[1,0]
	v_pk_mul_f32 v[66:67], v[66:67], v[116:117] op_sel:[0,1]
	v_pk_mul_f32 v[64:65], v[64:65], v[116:117] op_sel:[0,1]
	v_pk_mul_f32 v[54:55], v[54:55], v[118:119] op_sel_hi:[1,0]
	v_pk_mul_f32 v[52:53], v[52:53], v[118:119] op_sel_hi:[1,0]
	v_pk_mul_f32 v[58:59], v[58:59], v[118:119] op_sel:[0,1]
	v_pk_mul_f32 v[56:57], v[56:57], v[118:119] op_sel:[0,1]
	v_pk_mul_f32 v[46:47], v[46:47], v[120:121] op_sel_hi:[1,0]
	v_pk_mul_f32 v[44:45], v[44:45], v[120:121] op_sel_hi:[1,0]
	v_pk_mul_f32 v[50:51], v[50:51], v[120:121] op_sel:[0,1]
	v_pk_mul_f32 v[48:49], v[48:49], v[120:121] op_sel:[0,1]
	v_pk_mul_f32 v[38:39], v[38:39], v[122:123] op_sel_hi:[1,0]
	v_pk_mul_f32 v[36:37], v[36:37], v[122:123] op_sel_hi:[1,0]
	v_pk_mul_f32 v[42:43], v[42:43], v[122:123] op_sel:[0,1]
	v_pk_mul_f32 v[40:41], v[40:41], v[122:123] op_sel:[0,1]
	v_pk_mul_f32 v[22:23], v[22:23], v[124:125] op_sel_hi:[1,0]
	v_pk_mul_f32 v[20:21], v[20:21], v[124:125] op_sel_hi:[1,0]
	v_pk_mul_f32 v[34:35], v[34:35], v[124:125] op_sel:[0,1]
	v_pk_mul_f32 v[32:33], v[32:33], v[124:125] op_sel:[0,1]
	v_pk_mul_f32 v[18:19], v[18:19], v[126:127] op_sel_hi:[1,0]
	v_pk_mul_f32 v[16:17], v[16:17], v[126:127] op_sel_hi:[1,0]
	v_pk_mul_f32 v[30:31], v[30:31], v[126:127] op_sel:[0,1]
	v_pk_mul_f32 v[28:29], v[28:29], v[126:127] op_sel:[0,1]
	v_pk_mul_f32 v[10:11], v[10:11], v[128:129] op_sel_hi:[1,0]
	v_pk_mul_f32 v[8:9], v[8:9], v[128:129] op_sel_hi:[1,0]
	v_pk_mul_f32 v[26:27], v[26:27], v[128:129] op_sel:[0,1]
	v_pk_mul_f32 v[24:25], v[24:25], v[128:129] op_sel:[0,1]
	v_pk_mul_f32 v[6:7], v[6:7], v[130:131] op_sel_hi:[1,0]
	v_pk_mul_f32 v[4:5], v[4:5], v[130:131] op_sel_hi:[1,0]
	v_pk_mul_f32 v[14:15], v[14:15], v[130:131] op_sel:[0,1]
	v_pk_mul_f32 v[12:13], v[12:13], v[130:131] op_sel:[0,1]

;     ...
;     const float* src = W + (size_t)(k0 + 2 * q) * N + n0 + 4 * r16;
;     f32x4 v[16];
; #pragma unroll
;     for (int j = 0; j < 16; ++j) v[j] = *(const f32x4*)(src + (size_t)(8 * (j >> 1) + (j & 1)) * N);
;     if (nscale) { const f32x4 ns = *(const f32x4*)(nscale + n0 + 4 * r16);
; #pragma unroll
;         for (int j = 0; j < 16; ++j) v[j] = v[j] * ns; }
;     if (kscale) {
; #pragma unroll
;         for (int i = 0; i < 8; ++i) { const f32x2 g = *(const f32x2*)(kscale + k0 + 8 * i + 2 * q); v[2 * i] = v[2 * i] * g[0]; v[2 * i + 1] = v[2 * i + 1] * g[1]; } }
; __device__ __forceinline__ void weights_pass(const Args& a, LAS unsigned char* scr, int gw, int NGW, int lane, int pass) {
;     ...
;         if (r < I_G) { transpose_item<2>(a.in[I_WGATE] + (size_t)l * DM * DFF, DM, DFF, (bf16_t*)(wl + WL_GU), a.in[I_GFFN] + l * DM, nullptr, 0, scr, r, lane); continue; } r -= I_G;
.LBB0_640:
	s_andn2_b64 vcc, exec, s[4:5]
	s_cbranch_vccnz .LBB0_644
	v_readlane_b32 s36, v250, 0
	v_readlane_b32 s38, v250, 2
	v_readlane_b32 s39, v250, 3
	s_add_u32 s4, s38, s3
	s_addc_u32 s5, s39, s2
	s_add_i32 s2, s20, 0xd600
	s_and_b32 s3, s2, 0xffff
	s_mul_i32 s3, s3, 0xbe83
	s_lshr_b32 s6, s3, 23
	s_mul_i32 s3, s6, 0xac
	s_sub_i32 s2, s2, s3
	s_and_b32 s3, s2, 0xffff
	s_lshl_b32 s2, s6, 6
	v_or_b32_e32 v4, s2, v72
	v_mul_u32_u24_e32 v4, 0x2b00, v4
	v_lshlrev_b32_e32 v4, 2, v4
	v_mov_b32_e32 v5, v2
	v_lshl_add_u64 v[4:5], s[4:5], 0, v[4:5]
	s_lshl_b32 s14, s3, 8
	v_lshl_add_u64 v[4:5], v[4:5], 0, s[14:15]
	v_lshlrev_b32_e32 v6, 2, v68
	v_mov_b32_e32 v7, v2
	v_lshl_add_u64 v[4:5], v[4:5], 0, v[6:7]
	s_mov_b32 s4, 0xa000
	v_add_co_u32_e32 v6, vcc, s4, v4
	s_mov_b32 s4, 0x56000
	s_nop 0
	v_addc_co_u32_e32 v7, vcc, 0, v5, vcc
	global_load_dwordx4 v[60:63], v[4:5], off nt
	global_load_dwordx4 v[64:67], v[6:7], off offset:3072 nt
	v_add_co_u32_e32 v6, vcc, s4, v4
	s_mov_b32 s4, 0x60000
	s_nop 0
	v_addc_co_u32_e32 v7, vcc, 0, v5, vcc
	v_add_co_u32_e32 v8, vcc, s4, v4
	s_mov_b32 s4, 0xac000
	s_nop 0
	v_addc_co_u32_e32 v9, vcc, 0, v5, vcc
	global_load_dwordx4 v[52:55], v[6:7], off nt
	global_load_dwordx4 v[56:59], v[8:9], off offset:3072 nt
	v_add_co_u32_e32 v6, vcc, s4, v4
	s_mov_b32 s4, 0xb6000
	s_nop 0
	v_addc_co_u32_e32 v7, vcc, 0, v5, vcc
	v_add_co_u32_e32 v8, vcc, s4, v4
	s_mov_b32 s4, 0x102000
	s_nop 0
	v_addc_co_u32_e32 v9, vcc, 0, v5, vcc
	global_load_dwordx4 v[44:47], v[6:7], off nt
	global_load_dwordx4 v[48:51], v[8:9], off offset:3072 nt
	v_add_co_u32_e32 v6, vcc, s4, v4
	s_mov_b32 s4, 0x10c000
	s_nop 0
	v_addc_co_u32_e32 v7, vcc, 0, v5, vcc
	v_add_co_u32_e32 v8, vcc, s4, v4
	s_mov_b32 s4, 0x158000
	s_nop 0
	v_addc_co_u32_e32 v9, vcc, 0, v5, vcc
	global_load_dwordx4 v[36:39], v[6:7], off nt
	global_load_dwordx4 v[40:43], v[8:9], off offset:3072 nt
	v_add_co_u32_e32 v6, vcc, s4, v4
	s_mov_b32 s4, 0x162000
	s_nop 0
	v_addc_co_u32_e32 v7, vcc, 0, v5, vcc
	v_add_co_u32_e32 v8, vcc, s4, v4
	s_mov_b32 s4, 0x1ae000
	s_nop 0
	v_addc_co_u32_e32 v9, vcc, 0, v5, vcc
	global_load_dwordx4 v[20:23], v[6:7], off nt
	global_load_dwordx4 v[32:35], v[8:9], off offset:3072 nt
	v_add_co_u32_e32 v6, vcc, s4, v4
	s_mov_b32 s4, 0x1b8000
	s_nop 0
	v_addc_co_u32_e32 v7, vcc, 0, v5, vcc
	v_add_co_u32_e32 v8, vcc, s4, v4
	s_mov_b32 s4, 0x204000
	s_nop 0
	v_addc_co_u32_e32 v9, vcc, 0, v5, vcc
	global_load_dwordx4 v[16:19], v[6:7], off nt
	global_load_dwordx4 v[28:31], v[8:9], off offset:3072 nt
	v_add_co_u32_e32 v6, vcc, s4, v4
	v_readlane_b32 s4, v253, 7
	s_nop 0
	v_addc_co_u32_e32 v7, vcc, 0, v5, vcc
	v_add_co_u32_e32 v12, vcc, 0x20e000, v4
	v_readlane_b32 s5, v253, 8
	s_nop 0
	v_addc_co_u32_e32 v13, vcc, 0, v5, vcc
	global_load_dwordx4 v[8:11], v[6:7], off nt
	global_load_dwordx4 v[24:27], v[12:13], off offset:3072 nt
	v_add_co_u32_e32 v6, vcc, 0x25a000, v4
	v_readlane_b32 s37, v250, 1
	s_nop 0
	v_addc_co_u32_e32 v7, vcc, 0, v5, vcc
	v_add_co_u32_e32 v12, vcc, 0x264000, v4
	v_readlane_b32 s40, v250, 4
	s_nop 0
	v_addc_co_u32_e32 v13, vcc, 0, v5, vcc
	global_load_dwordx4 v[4:7], v[6:7], off nt
	s_nop 0
	global_load_dwordx4 v[12:15], v[12:13], off offset:3072 nt
	s_andn2_b64 vcc, exec, s[4:5]
	v_readlane_b32 s41, v250, 5
	v_readlane_b32 s42, v250, 6
	v_readlane_b32 s43, v250, 7
	s_cbranch_vccnz .LBB0_643
	s_lshl_b32 s4, s0, 12
	s_ashr_i32 s5, s4, 31
	s_lshl_b64 s[4:5], s[4:5], 2
	s_add_u32 s4, s36, s4
	s_addc_u32 s5, s37, s5
	s_lshl_b32 s6, s2, 2
	s_add_u32 s4, s4, s6
	s_addc_u32 s5, s5, 0
	v_lshlrev_b32_e32 v106, 2, v72
	global_load_dwordx2 v[116:117], v106, s[4:5]
	global_load_dwordx2 v[118:119], v106, s[4:5] offset:32
	global_load_dwordx2 v[120:121], v106, s[4:5] offset:64
	global_load_dwordx2 v[122:123], v106, s[4:5] offset:96
	global_load_dwordx2 v[124:125], v106, s[4:5] offset:128
	global_load_dwordx2 v[126:127], v106, s[4:5] offset:160
	global_load_dwordx2 v[128:129], v106, s[4:5] offset:192
	global_load_dwordx2 v[130:131], v106, s[4:5] offset:224
	s_waitcnt vmcnt(0)
	v_pk_mul_f32 v[62:63], v[62:63], v[116:117] op_sel_hi:[1,0]
	v_pk_mul_f32 v[60:61], v[60:61], v[116:117] op_sel_hi:[1,0]
	v_pk_mul_f32 v[66:67], v[66:67], v[116:117] op_sel:[0,1]
	v_pk_mul_f32 v[64:65], v[64:65], v[116:117] op_sel:[0,1]
	v_pk_mul_f32 v[54:55], v[54:55], v[118:119] op_sel_hi:[1,0]
	v_pk_mul_f32 v[52:53], v[52:53], v[118:119] op_sel_hi:[1,0]
	v_pk_mul_f32 v[58:59], v[58:59], v[118:119] op_sel:[0,1]
	v_pk_mul_f32 v[56:57], v[56:57], v[118:119] op_sel:[0,1]
	v_pk_mul_f32 v[46:47], v[46:47], v[120:121] op_sel_hi:[1,0]
	v_pk_mul_f32 v[44:45], v[44:45], v[120:121] op_sel_hi:[1,0]
	v_pk_mul_f32 v[50:51], v[50:51], v[120:121] op_sel:[0,1]
	v_pk_mul_f32 v[48:49], v[48:49], v[120:121] op_sel:[0,1]
	v_pk_mul_f32 v[38:39], v[38:39], v[122:123] op_sel_hi:[1,0]
	v_pk_mul_f32 v[36:37], v[36:37], v[122:123] op_sel_hi:[1,0]
	v_pk_mul_f32 v[42:43], v[42:43], v[122:123] op_sel:[0,1]
	v_pk_mul_f32 v[40:41], v[40:41], v[122:123] op_sel:[0,1]
	v_pk_mul_f32 v[22:23], v[22:23], v[124:125] op_sel_hi:[1,0]
	v_pk_mul_f32 v[20:21], v[20:21], v[124:125] op_sel_hi:[1,0]
	v_pk_mul_f32 v[34:35], v[34:35], v[124:125] op_sel:[0,1]
	v_pk_mul_f32 v[32:33], v[32:33], v[124:125] op_sel:[0,1]
	v_pk_mul_f32 v[18:19], v[18:19], v[126:127] op_sel_hi:[1,0]
	v_pk_mul_f32 v[16:17], v[16:17], v[126:127] op_sel_hi:[1,0]
	v_pk_mul_f32 v[30:31], v[30:31], v[126:127] op_sel:[0,1]
	v_pk_mul_f32 v[28:29], v[28:29], v[126:127] op_sel:[0,1]
	v_pk_mul_f32 v[10:11], v[10:11], v[128:129] op_sel_hi:[1,0]
	v_pk_mul_f32 v[8:9], v[8:9], v[128:129] op_sel_hi:[1,0]
	v_pk_mul_f32 v[26:27], v[26:27], v[128:129] op_sel:[0,1]
	v_pk_mul_f32 v[24:25], v[24:25], v[128:129] op_sel:[0,1]
	v_pk_mul_f32 v[6:7], v[6:7], v[130:131] op_sel_hi:[1,0]
	v_pk_mul_f32 v[4:5], v[4:5], v[130:131] op_sel_hi:[1,0]
	v_pk_mul_f32 v[14:15], v[14:15], v[130:131] op_sel:[0,1]
	v_pk_mul_f32 v[12:13], v[12:13], v[130:131] op_sel:[0,1]

;     ...
;     const float* src = W + (size_t)(k0 + 2 * q) * N + n0 + 4 * r16;
;     f32x4 v[16];
; #pragma unroll
;     for (int j = 0; j < 16; ++j) v[j] = *(const f32x4*)(src + (size_t)(8 * (j >> 1) + (j & 1)) * N);
;     if (nscale) { const f32x4 ns = *(const f32x4*)(nscale + n0 + 4 * r16);
; #pragma unroll
;         for (int j = 0; j < 16; ++j) v[j] = v[j] * ns; }
;     if (kscale) {
; #pragma unroll
;         for (int i = 0; i < 8; ++i) { const f32x2 g = *(const f32x2*)(kscale + k0 + 8 * i + 2 * q); v[2 * i] = v[2 * i] * g[0]; v[2 * i + 1] = v[2 * i + 1] * g[1]; } }
; __device__ __forceinline__ void weights_pass(const Args& a, LAS unsigned char* scr, int gw, int NGW, int lane, int pass) {
;     ...
;         if (r < I_QM) { transpose_item<1>(a.in[I_WVM] + (size_t)l * DM * MW, DM, MW, (bf16_t*)(ws + WS_WKV) + (size_t)l * 1024 * DM, a.in[I_GMEM] + l * DM, nullptr, 512, scr, r, lane); continue; } r -= I_QM;
.LBB0_648:
	s_andn2_b64 vcc, exec, s[4:5]
	s_cbranch_vccnz .LBB0_652
	v_readlane_b32 s36, v250, 46
	s_lshl_b64 s[4:5], s[0:1], 23
	v_readlane_b32 s44, v250, 54
	v_readlane_b32 s45, v250, 55
	s_add_u32 s6, s44, s4
	s_mul_i32 s2, s0, 0xfffaa800
	s_addc_u32 s7, s45, s5
	s_add_i32 s2, s9, s2
	s_addk_i32 s2, 0xe000
	s_and_b32 s2, s2, 0x7ffc0
	v_or_b32_e32 v4, s2, v72
	s_and_b32 s3, s16, 0x1c0
	v_lshlrev_b32_e32 v4, 11, v4
	v_mov_b32_e32 v5, v2
	v_lshl_add_u64 v[4:5], s[6:7], 0, v[4:5]
	s_lshl_b32 s14, s3, 2
	v_lshl_add_u64 v[4:5], v[4:5], 0, s[14:15]
	v_lshlrev_b32_e32 v6, 2, v68
	v_mov_b32_e32 v7, v2
	v_lshl_add_u64 v[4:5], v[4:5], 0, v[6:7]
	s_movk_i32 s6, 0x4000
	v_add_co_u32_e32 v6, vcc, s6, v4
	s_mov_b32 s6, 0x8000
	s_nop 0
	v_addc_co_u32_e32 v7, vcc, 0, v5, vcc
	global_load_dwordx4 v[60:63], v[4:5], off nt
	global_load_dwordx4 v[64:67], v[4:5], off offset:2048 nt
	global_load_dwordx4 v[52:55], v[6:7], off nt
	global_load_dwordx4 v[56:59], v[6:7], off offset:2048 nt
	v_add_co_u32_e32 v6, vcc, s6, v4
	s_mov_b32 s6, 0x10000
	s_nop 0
	v_addc_co_u32_e32 v7, vcc, 0, v5, vcc
	global_load_dwordx4 v[44:47], v[6:7], off nt
	global_load_dwordx4 v[48:51], v[6:7], off offset:2048 nt
	v_add_co_u32_e32 v6, vcc, 0xc000, v4
	v_readlane_b32 s38, v250, 48
	s_nop 0
	v_addc_co_u32_e32 v7, vcc, 0, v5, vcc
	global_load_dwordx4 v[36:39], v[6:7], off nt
	global_load_dwordx4 v[40:43], v[6:7], off offset:2048 nt
	v_add_co_u32_e32 v6, vcc, s6, v4
	s_mov_b32 s6, 0x14000
	s_nop 0
	v_addc_co_u32_e32 v7, vcc, 0, v5, vcc
	global_load_dwordx4 v[28:31], v[6:7], off nt
	global_load_dwordx4 v[32:35], v[6:7], off offset:2048 nt
	v_add_co_u32_e32 v6, vcc, s6, v4
	v_readlane_b32 s6, v253, 9
	s_nop 0
	v_addc_co_u32_e32 v7, vcc, 0, v5, vcc
	global_load_dwordx4 v[20:23], v[6:7], off nt
	global_load_dwordx4 v[24:27], v[6:7], off offset:2048 nt
	v_add_co_u32_e32 v6, vcc, 0x18000, v4
	v_readlane_b32 s7, v253, 10
	s_nop 0
	v_addc_co_u32_e32 v7, vcc, 0, v5, vcc
	v_add_co_u32_e32 v8, vcc, 0x1c000, v4
	global_load_dwordx4 v[12:15], v[6:7], off nt
	global_load_dwordx4 v[16:19], v[6:7], off offset:2048 nt
	v_addc_co_u32_e32 v9, vcc, 0, v5, vcc
	global_load_dwordx4 v[4:7], v[8:9], off nt
	s_nop 0
	global_load_dwordx4 v[8:11], v[8:9], off offset:2048 nt
	v_readlane_b32 s39, v250, 49
	s_andn2_b64 vcc, exec, s[6:7]
	v_readlane_b32 s37, v250, 47
	v_readlane_b32 s40, v250, 50
	v_readlane_b32 s41, v250, 51
	v_readlane_b32 s42, v250, 52
	v_readlane_b32 s43, v250, 53
	v_readlane_b32 s46, v250, 56
	v_readlane_b32 s47, v250, 57
	v_readlane_b32 s48, v250, 58
	v_readlane_b32 s49, v250, 59
	v_readlane_b32 s50, v250, 60
	v_readlane_b32 s51, v250, 61
	s_cbranch_vccnz .LBB0_651
	s_lshl_b32 s6, s0, 12
	s_ashr_i32 s7, s6, 31
	s_lshl_b64 s[6:7], s[6:7], 2
	s_add_u32 s6, s38, s6
	s_addc_u32 s7, s39, s7
	s_lshl_b32 s14, s2, 2
	s_add_u32 s6, s6, s14
	s_addc_u32 s7, s7, 0
	v_lshlrev_b32_e32 v106, 2, v72
	global_load_dwordx2 v[116:117], v106, s[6:7]
	global_load_dwordx2 v[118:119], v106, s[6:7] offset:32
	global_load_dwordx2 v[120:121], v106, s[6:7] offset:64
	global_load_dwordx2 v[122:123], v106, s[6:7] offset:96
	global_load_dwordx2 v[124:125], v106, s[6:7] offset:128
	global_load_dwordx2 v[126:127], v106, s[6:7] offset:160
	global_load_dwordx2 v[128:129], v106, s[6:7] offset:192
	global_load_dwordx2 v[130:131], v106, s[6:7] offset:224
	s_waitcnt vmcnt(0)
	v_pk_mul_f32 v[62:63], v[62:63], v[116:117] op_sel_hi:[1,0]
	v_pk_mul_f32 v[60:61], v[60:61], v[116:117] op_sel_hi:[1,0]
	v_pk_mul_f32 v[66:67], v[66:67], v[116:117] op_sel:[0,1]
	v_pk_mul_f32 v[64:65], v[64:65], v[116:117] op_sel:[0,1]
	v_pk_mul_f32 v[54:55], v[54:55], v[118:119] op_sel_hi:[1,0]
	v_pk_mul_f32 v[52:53], v[52:53], v[118:119] op_sel_hi:[1,0]
	v_pk_mul_f32 v[58:59], v[58:59], v[118:119] op_sel:[0,1]
	v_pk_mul_f32 v[56:57], v[56:57], v[118:119] op_sel:[0,1]
	v_pk_mul_f32 v[46:47], v[46:47], v[120:121] op_sel_hi:[1,0]
	v_pk_mul_f32 v[44:45], v[44:45], v[120:121] op_sel_hi:[1,0]
	v_pk_mul_f32 v[50:51], v[50:51], v[120:121] op_sel:[0,1]
	v_pk_mul_f32 v[48:49], v[48:49], v[120:121] op_sel:[0,1]
	v_pk_mul_f32 v[38:39], v[38:39], v[122:123] op_sel_hi:[1,0]
	v_pk_mul_f32 v[36:37], v[36:37], v[122:123] op_sel_hi:[1,0]
	v_pk_mul_f32 v[42:43], v[42:43], v[122:123] op_sel:[0,1]
	v_pk_mul_f32 v[40:41], v[40:41], v[122:123] op_sel:[0,1]
	v_pk_mul_f32 v[30:31], v[30:31], v[124:125] op_sel_hi:[1,0]
	v_pk_mul_f32 v[28:29], v[28:29], v[124:125] op_sel_hi:[1,0]
	v_pk_mul_f32 v[34:35], v[34:35], v[124:125] op_sel:[0,1]
	v_pk_mul_f32 v[32:33], v[32:33], v[124:125] op_sel:[0,1]
	v_pk_mul_f32 v[22:23], v[22:23], v[126:127] op_sel_hi:[1,0]
	v_pk_mul_f32 v[20:21], v[20:21], v[126:127] op_sel_hi:[1,0]
	v_pk_mul_f32 v[26:27], v[26:27], v[126:127] op_sel:[0,1]
	v_pk_mul_f32 v[24:25], v[24:25], v[126:127] op_sel:[0,1]
	v_pk_mul_f32 v[14:15], v[14:15], v[128:129] op_sel_hi:[1,0]
	v_pk_mul_f32 v[12:13], v[12:13], v[128:129] op_sel_hi:[1,0]
	v_pk_mul_f32 v[18:19], v[18:19], v[128:129] op_sel:[0,1]
	v_pk_mul_f32 v[16:17], v[16:17], v[128:129] op_sel:[0,1]
	v_pk_mul_f32 v[6:7], v[6:7], v[130:131] op_sel_hi:[1,0]
	v_pk_mul_f32 v[4:5], v[4:5], v[130:131] op_sel_hi:[1,0]
	v_pk_mul_f32 v[10:11], v[10:11], v[130:131] op_sel:[0,1]
	v_pk_mul_f32 v[8:9], v[8:9], v[130:131] op_sel:[0,1]

;     ...
;     const float* src = W + (size_t)(k0 + 2 * q) * N + n0 + 4 * r16;
;     f32x4 v[16];
; #pragma unroll
;     for (int j = 0; j < 16; ++j) v[j] = *(const f32x4*)(src + (size_t)(8 * (j >> 1) + (j & 1)) * N);
;     if (nscale) { const f32x4 ns = *(const f32x4*)(nscale + n0 + 4 * r16);
; #pragma unroll
;         for (int j = 0; j < 16; ++j) v[j] = v[j] * ns; }
;     if (kscale) {
; #pragma unroll
;         for (int i = 0; i < 8; ++i) { const f32x2 g = *(const f32x2*)(kscale + k0 + 8 * i + 2 * q); v[2 * i] = v[2 * i] * g[0]; v[2 * i + 1] = v[2 * i + 1] * g[1]; } }
; __device__ __forceinline__ void weights_pass(const Args& a, LAS unsigned char* scr, int gw, int NGW, int lane, int pass) {
;     ...
;         if (r < I_QM) { transpose_item<1>(a.in[I_WKM] + (size_t)l * DM * MW, DM, MW, (bf16_t*)(ws + WS_WKV) + (size_t)l * 1024 * DM, a.in[I_GMEM] + l * DM, nullptr, 0, scr, r, lane); continue; } r -= I_QM;
.LBB0_653:
	s_andn2_b64 vcc, exec, s[4:5]
	s_cbranch_vccnz .LBB0_657
	v_readlane_b32 s36, v250, 46
	s_lshl_b64 s[4:5], s[0:1], 23
	v_readlane_b32 s42, v250, 52
	v_readlane_b32 s43, v250, 53
	s_add_u32 s6, s42, s4
	s_mul_i32 s2, s0, 0xfffaa800
	s_addc_u32 s7, s43, s5
	s_add_i32 s2, s9, s2
	s_addk_i32 s2, 0xf000
	s_and_b32 s3, s2, 0x7ffc0
	s_mul_i32 s2, s0, 0xffd54000
	s_add_i32 s2, s16, s2
	v_or_b32_e32 v4, s3, v72
	s_and_b32 s14, s2, 0x1c0
	v_lshlrev_b32_e32 v4, 11, v4
	v_mov_b32_e32 v5, v2
	v_lshl_add_u64 v[4:5], s[6:7], 0, v[4:5]
	s_lshl_b32 s14, s14, 2
	v_lshl_add_u64 v[4:5], v[4:5], 0, s[14:15]
	v_lshlrev_b32_e32 v6, 2, v68
	v_mov_b32_e32 v7, v2
	v_lshl_add_u64 v[4:5], v[4:5], 0, v[6:7]
	s_movk_i32 s6, 0x4000
	v_add_co_u32_e32 v6, vcc, s6, v4
	s_mov_b32 s6, 0x8000
	s_nop 0
	v_addc_co_u32_e32 v7, vcc, 0, v5, vcc
	global_load_dwordx4 v[60:63], v[4:5], off nt
	global_load_dwordx4 v[64:67], v[4:5], off offset:2048 nt
	global_load_dwordx4 v[52:55], v[6:7], off nt
	global_load_dwordx4 v[56:59], v[6:7], off offset:2048 nt
	v_add_co_u32_e32 v6, vcc, s6, v4
	s_mov_b32 s6, 0x10000
	s_nop 0
	v_addc_co_u32_e32 v7, vcc, 0, v5, vcc
	global_load_dwordx4 v[44:47], v[6:7], off nt
	global_load_dwordx4 v[48:51], v[6:7], off offset:2048 nt
	v_add_co_u32_e32 v6, vcc, 0xc000, v4
	v_readlane_b32 s38, v250, 48
	s_nop 0
	v_addc_co_u32_e32 v7, vcc, 0, v5, vcc
	global_load_dwordx4 v[36:39], v[6:7], off nt
	global_load_dwordx4 v[40:43], v[6:7], off offset:2048 nt
	v_add_co_u32_e32 v6, vcc, s6, v4
	s_mov_b32 s6, 0x14000
	s_nop 0
	v_addc_co_u32_e32 v7, vcc, 0, v5, vcc
	global_load_dwordx4 v[28:31], v[6:7], off nt
	global_load_dwordx4 v[32:35], v[6:7], off offset:2048 nt
	v_add_co_u32_e32 v6, vcc, s6, v4
	v_readlane_b32 s6, v253, 9
	s_nop 0
	v_addc_co_u32_e32 v7, vcc, 0, v5, vcc
	global_load_dwordx4 v[20:23], v[6:7], off nt
	global_load_dwordx4 v[24:27], v[6:7], off offset:2048 nt
	v_add_co_u32_e32 v6, vcc, 0x18000, v4
	v_readlane_b32 s7, v253, 10
	s_nop 0
	v_addc_co_u32_e32 v7, vcc, 0, v5, vcc
	v_add_co_u32_e32 v8, vcc, 0x1c000, v4
	global_load_dwordx4 v[12:15], v[6:7], off nt
	global_load_dwordx4 v[16:19], v[6:7], off offset:2048 nt
	v_addc_co_u32_e32 v9, vcc, 0, v5, vcc
	global_load_dwordx4 v[4:7], v[8:9], off nt
	s_nop 0
	global_load_dwordx4 v[8:11], v[8:9], off offset:2048 nt
	v_readlane_b32 s39, v250, 49
	s_andn2_b64 vcc, exec, s[6:7]
	v_readlane_b32 s37, v250, 47
	v_readlane_b32 s40, v250, 50
	v_readlane_b32 s41, v250, 51
	v_readlane_b32 s44, v250, 54
	v_readlane_b32 s45, v250, 55
	v_readlane_b32 s46, v250, 56
	v_readlane_b32 s47, v250, 57
	v_readlane_b32 s48, v250, 58
	v_readlane_b32 s49, v250, 59
	v_readlane_b32 s50, v250, 60
	v_readlane_b32 s51, v250, 61
	s_cbranch_vccnz .LBB0_656
	s_lshl_b32 s6, s0, 12
	s_ashr_i32 s7, s6, 31
	s_lshl_b64 s[6:7], s[6:7], 2
	s_add_u32 s6, s38, s6
	s_addc_u32 s7, s39, s7
	s_lshl_b32 s14, s3, 2
	s_add_u32 s6, s6, s14
	s_addc_u32 s7, s7, 0
	v_lshlrev_b32_e32 v106, 2, v72
	global_load_dwordx2 v[116:117], v106, s[6:7]
	global_load_dwordx2 v[118:119], v106, s[6:7] offset:32
	global_load_dwordx2 v[120:121], v106, s[6:7] offset:64
	global_load_dwordx2 v[122:123], v106, s[6:7] offset:96
	global_load_dwordx2 v[124:125], v106, s[6:7] offset:128
	global_load_dwordx2 v[126:127], v106, s[6:7] offset:160
	global_load_dwordx2 v[128:129], v106, s[6:7] offset:192
	global_load_dwordx2 v[130:131], v106, s[6:7] offset:224
	s_waitcnt vmcnt(0)
	v_pk_mul_f32 v[62:63], v[62:63], v[116:117] op_sel_hi:[1,0]
	v_pk_mul_f32 v[60:61], v[60:61], v[116:117] op_sel_hi:[1,0]
	v_pk_mul_f32 v[66:67], v[66:67], v[116:117] op_sel:[0,1]
	v_pk_mul_f32 v[64:65], v[64:65], v[116:117] op_sel:[0,1]
	v_pk_mul_f32 v[54:55], v[54:55], v[118:119] op_sel_hi:[1,0]
	v_pk_mul_f32 v[52:53], v[52:53], v[118:119] op_sel_hi:[1,0]
	v_pk_mul_f32 v[58:59], v[58:59], v[118:119] op_sel:[0,1]
	v_pk_mul_f32 v[56:57], v[56:57], v[118:119] op_sel:[0,1]
	v_pk_mul_f32 v[46:47], v[46:47], v[120:121] op_sel_hi:[1,0]
	v_pk_mul_f32 v[44:45], v[44:45], v[120:121] op_sel_hi:[1,0]
	v_pk_mul_f32 v[50:51], v[50:51], v[120:121] op_sel:[0,1]
	v_pk_mul_f32 v[48:49], v[48:49], v[120:121] op_sel:[0,1]
	v_pk_mul_f32 v[38:39], v[38:39], v[122:123] op_sel_hi:[1,0]
	v_pk_mul_f32 v[36:37], v[36:37], v[122:123] op_sel_hi:[1,0]
	v_pk_mul_f32 v[42:43], v[42:43], v[122:123] op_sel:[0,1]
	v_pk_mul_f32 v[40:41], v[40:41], v[122:123] op_sel:[0,1]
	v_pk_mul_f32 v[30:31], v[30:31], v[124:125] op_sel_hi:[1,0]
	v_pk_mul_f32 v[28:29], v[28:29], v[124:125] op_sel_hi:[1,0]
	v_pk_mul_f32 v[34:35], v[34:35], v[124:125] op_sel:[0,1]
	v_pk_mul_f32 v[32:33], v[32:33], v[124:125] op_sel:[0,1]
	v_pk_mul_f32 v[22:23], v[22:23], v[126:127] op_sel_hi:[1,0]
	v_pk_mul_f32 v[20:21], v[20:21], v[126:127] op_sel_hi:[1,0]
	v_pk_mul_f32 v[26:27], v[26:27], v[126:127] op_sel:[0,1]
	v_pk_mul_f32 v[24:25], v[24:25], v[126:127] op_sel:[0,1]
	v_pk_mul_f32 v[14:15], v[14:15], v[128:129] op_sel_hi:[1,0]
	v_pk_mul_f32 v[12:13], v[12:13], v[128:129] op_sel_hi:[1,0]
	v_pk_mul_f32 v[18:19], v[18:19], v[128:129] op_sel:[0,1]
	v_pk_mul_f32 v[16:17], v[16:17], v[128:129] op_sel:[0,1]
	v_pk_mul_f32 v[6:7], v[6:7], v[130:131] op_sel_hi:[1,0]
	v_pk_mul_f32 v[4:5], v[4:5], v[130:131] op_sel_hi:[1,0]
	v_pk_mul_f32 v[10:11], v[10:11], v[130:131] op_sel:[0,1]
	v_pk_mul_f32 v[8:9], v[8:9], v[130:131] op_sel:[0,1]

;     ...
;     const float* src = W + (size_t)(k0 + 2 * q) * N + n0 + 4 * r16;
;     f32x4 v[16];
; #pragma unroll
;     for (int j = 0; j < 16; ++j) v[j] = *(const f32x4*)(src + (size_t)(8 * (j >> 1) + (j & 1)) * N);
;     if (nscale) { const f32x4 ns = *(const f32x4*)(nscale + n0 + 4 * r16);
; #pragma unroll
;         for (int j = 0; j < 16; ++j) v[j] = v[j] * ns; }
;     if (kscale) {
; #pragma unroll
;         for (int i = 0; i < 8; ++i) { const f32x2 g = *(const f32x2*)(kscale + k0 + 8 * i + 2 * q); v[2 * i] = v[2 * i] * g[0]; v[2 * i + 1] = v[2 * i + 1] * g[1]; } }
; __device__ __forceinline__ void weights_pass(const Args& a, LAS unsigned char* scr, int gw, int NGW, int lane, int pass) {
;     ...
;         if (r < I_QM) { transpose_item<0>(a.in[I_WQM] + (size_t)l * DM * MW, DM, MW, (bf16_t*)(wl + WL_Q), a.in[I_GCROSS] + l * DM, nullptr, 0, scr, r, lane); continue; } r -= I_QM;
.LBB0_658:
	s_andn2_b64 vcc, exec, s[4:5]
	s_cbranch_vccnz .LBB0_662
	v_readlane_b32 s36, v250, 46
	s_lshl_b64 s[2:3], s[0:1], 23
	v_readlane_b32 s40, v250, 50
	v_readlane_b32 s41, v250, 51
	s_add_u32 s4, s40, s2
	s_mul_i32 s2, s0, 0xfffaa800
	s_addc_u32 s5, s41, s3
	s_add_i32 s2, s9, s2
	s_and_b32 s2, s2, 0x7ffc0
	s_lshl_b32 s3, s20, 6
	v_or_b32_e32 v4, s2, v72
	s_and_b32 s3, s3, 0x1c0
	v_lshlrev_b32_e32 v4, 11, v4
	v_mov_b32_e32 v5, v2
	v_lshl_add_u64 v[4:5], s[4:5], 0, v[4:5]
	s_lshl_b32 s14, s3, 2
	v_lshl_add_u64 v[4:5], v[4:5], 0, s[14:15]
	v_lshlrev_b32_e32 v6, 2, v68
	v_mov_b32_e32 v7, v2
	v_lshl_add_u64 v[4:5], v[4:5], 0, v[6:7]
	s_movk_i32 s4, 0x4000
	v_add_co_u32_e32 v6, vcc, s4, v4
	s_mov_b32 s4, 0x8000
	s_nop 0
	v_addc_co_u32_e32 v7, vcc, 0, v5, vcc
	global_load_dwordx4 v[60:63], v[4:5], off nt
	global_load_dwordx4 v[64:67], v[4:5], off offset:2048 nt
	global_load_dwordx4 v[52:55], v[6:7], off nt
	global_load_dwordx4 v[56:59], v[6:7], off offset:2048 nt
	v_add_co_u32_e32 v6, vcc, s4, v4
	s_mov_b32 s4, 0x10000
	s_nop 0
	v_addc_co_u32_e32 v7, vcc, 0, v5, vcc
	global_load_dwordx4 v[44:47], v[6:7], off nt
	global_load_dwordx4 v[48:51], v[6:7], off offset:2048 nt
	v_add_co_u32_e32 v6, vcc, 0xc000, v4
	v_readlane_b32 s37, v250, 47
	s_nop 0
	v_addc_co_u32_e32 v7, vcc, 0, v5, vcc
	global_load_dwordx4 v[36:39], v[6:7], off nt
	global_load_dwordx4 v[40:43], v[6:7], off offset:2048 nt
	v_add_co_u32_e32 v6, vcc, s4, v4
	s_mov_b32 s4, 0x14000
	s_nop 0
	v_addc_co_u32_e32 v7, vcc, 0, v5, vcc
	global_load_dwordx4 v[28:31], v[6:7], off nt
	global_load_dwordx4 v[32:35], v[6:7], off offset:2048 nt
	v_add_co_u32_e32 v6, vcc, s4, v4
	v_readlane_b32 s4, v253, 11
	s_nop 0
	v_addc_co_u32_e32 v7, vcc, 0, v5, vcc
	global_load_dwordx4 v[20:23], v[6:7], off nt
	global_load_dwordx4 v[24:27], v[6:7], off offset:2048 nt
	v_add_co_u32_e32 v6, vcc, 0x18000, v4
	v_readlane_b32 s5, v253, 12
	s_nop 0
	v_addc_co_u32_e32 v7, vcc, 0, v5, vcc
	v_add_co_u32_e32 v8, vcc, 0x1c000, v4
	global_load_dwordx4 v[12:15], v[6:7], off nt
	global_load_dwordx4 v[16:19], v[6:7], off offset:2048 nt
	v_addc_co_u32_e32 v9, vcc, 0, v5, vcc
	global_load_dwordx4 v[4:7], v[8:9], off nt
	s_nop 0
	global_load_dwordx4 v[8:11], v[8:9], off offset:2048 nt
	s_andn2_b64 vcc, exec, s[4:5]
	v_readlane_b32 s38, v250, 48
	v_readlane_b32 s39, v250, 49
	v_readlane_b32 s42, v250, 52
	v_readlane_b32 s43, v250, 53
	v_readlane_b32 s44, v250, 54
	v_readlane_b32 s45, v250, 55
	v_readlane_b32 s46, v250, 56
	v_readlane_b32 s47, v250, 57
	v_readlane_b32 s48, v250, 58
	v_readlane_b32 s49, v250, 59
	v_readlane_b32 s50, v250, 60
	v_readlane_b32 s51, v250, 61
	s_cbranch_vccnz .LBB0_661
	s_lshl_b32 s4, s0, 12
	s_ashr_i32 s5, s4, 31
	s_lshl_b64 s[4:5], s[4:5], 2
	s_add_u32 s4, s36, s4
	s_addc_u32 s5, s37, s5
	s_lshl_b32 s6, s2, 2
	s_add_u32 s4, s4, s6
	s_addc_u32 s5, s5, 0
	v_lshlrev_b32_e32 v106, 2, v72
	global_load_dwordx2 v[116:117], v106, s[4:5]
	global_load_dwordx2 v[118:119], v106, s[4:5] offset:32
	global_load_dwordx2 v[120:121], v106, s[4:5] offset:64
	global_load_dwordx2 v[122:123], v106, s[4:5] offset:96
	global_load_dwordx2 v[124:125], v106, s[4:5] offset:128
	global_load_dwordx2 v[126:127], v106, s[4:5] offset:160
	global_load_dwordx2 v[128:129], v106, s[4:5] offset:192
	global_load_dwordx2 v[130:131], v106, s[4:5] offset:224
	s_waitcnt vmcnt(0)
	v_pk_mul_f32 v[62:63], v[62:63], v[116:117] op_sel_hi:[1,0]
	v_pk_mul_f32 v[60:61], v[60:61], v[116:117] op_sel_hi:[1,0]
	v_pk_mul_f32 v[66:67], v[66:67], v[116:117] op_sel:[0,1]
	v_pk_mul_f32 v[64:65], v[64:65], v[116:117] op_sel:[0,1]
	v_pk_mul_f32 v[54:55], v[54:55], v[118:119] op_sel_hi:[1,0]
	v_pk_mul_f32 v[52:53], v[52:53], v[118:119] op_sel_hi:[1,0]
	v_pk_mul_f32 v[58:59], v[58:59], v[118:119] op_sel:[0,1]
	v_pk_mul_f32 v[56:57], v[56:57], v[118:119] op_sel:[0,1]
	v_pk_mul_f32 v[46:47], v[46:47], v[120:121] op_sel_hi:[1,0]
	v_pk_mul_f32 v[44:45], v[44:45], v[120:121] op_sel_hi:[1,0]
	v_pk_mul_f32 v[50:51], v[50:51], v[120:121] op_sel:[0,1]
	v_pk_mul_f32 v[48:49], v[48:49], v[120:121] op_sel:[0,1]
	v_pk_mul_f32 v[38:39], v[38:39], v[122:123] op_sel_hi:[1,0]
	v_pk_mul_f32 v[36:37], v[36:37], v[122:123] op_sel_hi:[1,0]
	v_pk_mul_f32 v[42:43], v[42:43], v[122:123] op_sel:[0,1]
	v_pk_mul_f32 v[40:41], v[40:41], v[122:123] op_sel:[0,1]
	v_pk_mul_f32 v[30:31], v[30:31], v[124:125] op_sel_hi:[1,0]
	v_pk_mul_f32 v[28:29], v[28:29], v[124:125] op_sel_hi:[1,0]
	v_pk_mul_f32 v[34:35], v[34:35], v[124:125] op_sel:[0,1]
	v_pk_mul_f32 v[32:33], v[32:33], v[124:125] op_sel:[0,1]
	v_pk_mul_f32 v[22:23], v[22:23], v[126:127] op_sel_hi:[1,0]
	v_pk_mul_f32 v[20:21], v[20:21], v[126:127] op_sel_hi:[1,0]
	v_pk_mul_f32 v[26:27], v[26:27], v[126:127] op_sel:[0,1]
	v_pk_mul_f32 v[24:25], v[24:25], v[126:127] op_sel:[0,1]
	v_pk_mul_f32 v[14:15], v[14:15], v[128:129] op_sel_hi:[1,0]
	v_pk_mul_f32 v[12:13], v[12:13], v[128:129] op_sel_hi:[1,0]
	v_pk_mul_f32 v[18:19], v[18:19], v[128:129] op_sel:[0,1]
	v_pk_mul_f32 v[16:17], v[16:17], v[128:129] op_sel:[0,1]
	v_pk_mul_f32 v[6:7], v[6:7], v[130:131] op_sel_hi:[1,0]
	v_pk_mul_f32 v[4:5], v[4:5], v[130:131] op_sel_hi:[1,0]
	v_pk_mul_f32 v[10:11], v[10:11], v[130:131] op_sel:[0,1]
	v_pk_mul_f32 v[8:9], v[8:9], v[130:131] op_sel:[0,1]

;     ...
;     const float* src = W + (size_t)(k0 + 2 * q) * N + n0 + 4 * r16;
;     f32x4 v[16];
; #pragma unroll
;     for (int j = 0; j < 16; ++j) v[j] = *(const f32x4*)(src + (size_t)(8 * (j >> 1) + (j & 1)) * N);
;     if (nscale) { const f32x4 ns = *(const f32x4*)(nscale + n0 + 4 * r16);
; #pragma unroll
;         for (int j = 0; j < 16; ++j) v[j] = v[j] * ns; }
;     if (kscale) {
; #pragma unroll
;         for (int i = 0; i < 8; ++i) { const f32x2 g = *(const f32x2*)(kscale + k0 + 8 * i + 2 * q); v[2 * i] = v[2 * i] * g[0]; v[2 * i + 1] = v[2 * i + 1] * g[1]; } }
; __device__ __forceinline__ void weights_pass(const Args& a, LAS unsigned char* scr, int gw, int NGW, int lane, int pass) {
;     ...
;         if (r < I_G) { transpose_item<3>(a.in[I_WUP] + (size_t)l * DM * DFF, DM, DFF, (bf16_t*)(wl + WL_GU), a.in[I_GFFN] + l * DM, nullptr, 0, scr, r, lane); continue; } r -= I_G;
.LBB0_1679:
	s_andn2_b64 vcc, exec, s[6:7]
	s_cbranch_vccnz .LBB0_1683
	v_readlane_b32 s36, v250, 0
	v_readlane_b32 s40, v250, 4
	v_readlane_b32 s41, v250, 5
	s_add_u32 s6, s40, s3
	s_addc_u32 s7, s41, s2
	s_add_i32 s8, s21, 0xab00
	s_and_b32 s9, s8, 0xffff
	s_mul_i32 s9, s9, 0xbe83
	s_lshr_b32 s14, s9, 23
	s_mul_i32 s9, s14, 0xac
	s_sub_i32 s8, s8, s9
	s_and_b32 s9, s8, 0xffff
	s_lshl_b32 s8, s14, 6
	v_or_b32_e32 v4, s8, v72
	v_mul_u32_u24_e32 v4, 0x2b00, v4
	v_lshlrev_b32_e32 v4, 2, v4
	v_mov_b32_e32 v5, v2
	v_lshl_add_u64 v[4:5], s[6:7], 0, v[4:5]
	s_lshl_b32 s14, s9, 8
	v_lshl_add_u64 v[4:5], v[4:5], 0, s[14:15]
	v_lshlrev_b32_e32 v6, 2, v68
	v_mov_b32_e32 v7, v2
	v_lshl_add_u64 v[4:5], v[4:5], 0, v[6:7]
	s_mov_b32 s6, 0xa000
	v_add_co_u32_e32 v6, vcc, s6, v4
	s_mov_b32 s6, 0x56000
	s_nop 0
	v_addc_co_u32_e32 v7, vcc, 0, v5, vcc
	global_load_dwordx4 v[60:63], v[4:5], off nt
	global_load_dwordx4 v[64:67], v[6:7], off offset:3072 nt
	v_add_co_u32_e32 v6, vcc, s6, v4
	s_mov_b32 s6, 0x60000
	s_nop 0
	v_addc_co_u32_e32 v7, vcc, 0, v5, vcc
	v_add_co_u32_e32 v8, vcc, s6, v4
	s_mov_b32 s6, 0xac000
	s_nop 0
	v_addc_co_u32_e32 v9, vcc, 0, v5, vcc
	global_load_dwordx4 v[52:55], v[6:7], off nt
	global_load_dwordx4 v[56:59], v[8:9], off offset:3072 nt
	v_add_co_u32_e32 v6, vcc, s6, v4
	s_mov_b32 s6, 0xb6000
	s_nop 0
	v_addc_co_u32_e32 v7, vcc, 0, v5, vcc
	v_add_co_u32_e32 v8, vcc, s6, v4
	s_mov_b32 s6, 0x102000
	s_nop 0
	v_addc_co_u32_e32 v9, vcc, 0, v5, vcc
	global_load_dwordx4 v[44:47], v[6:7], off nt
	global_load_dwordx4 v[48:51], v[8:9], off offset:3072 nt
	v_add_co_u32_e32 v6, vcc, s6, v4
	s_mov_b32 s6, 0x10c000
	s_nop 0
	v_addc_co_u32_e32 v7, vcc, 0, v5, vcc
	v_add_co_u32_e32 v8, vcc, s6, v4
	s_mov_b32 s6, 0x158000
	s_nop 0
	v_addc_co_u32_e32 v9, vcc, 0, v5, vcc
	global_load_dwordx4 v[36:39], v[6:7], off nt
	global_load_dwordx4 v[40:43], v[8:9], off offset:3072 nt
	v_add_co_u32_e32 v6, vcc, s6, v4
	s_mov_b32 s6, 0x162000
	s_nop 0
	v_addc_co_u32_e32 v7, vcc, 0, v5, vcc
	v_add_co_u32_e32 v8, vcc, s6, v4
	s_mov_b32 s6, 0x1ae000
	s_nop 0
	v_addc_co_u32_e32 v9, vcc, 0, v5, vcc
	global_load_dwordx4 v[20:23], v[6:7], off nt
	global_load_dwordx4 v[32:35], v[8:9], off offset:3072 nt
	v_add_co_u32_e32 v6, vcc, s6, v4
	s_mov_b32 s6, 0x1b8000
	s_nop 0
	v_addc_co_u32_e32 v7, vcc, 0, v5, vcc
	v_add_co_u32_e32 v8, vcc, s6, v4
	s_mov_b32 s6, 0x204000
	s_nop 0
	v_addc_co_u32_e32 v9, vcc, 0, v5, vcc
	global_load_dwordx4 v[16:19], v[6:7], off nt
	global_load_dwordx4 v[28:31], v[8:9], off offset:3072 nt
	v_add_co_u32_e32 v6, vcc, s6, v4
	v_readlane_b32 s6, v253, 7
	s_nop 0
	v_addc_co_u32_e32 v7, vcc, 0, v5, vcc
	v_add_co_u32_e32 v12, vcc, 0x20e000, v4
	v_readlane_b32 s7, v253, 8
	s_nop 0
	v_addc_co_u32_e32 v13, vcc, 0, v5, vcc
	global_load_dwordx4 v[8:11], v[6:7], off nt
	global_load_dwordx4 v[24:27], v[12:13], off offset:3072 nt
	v_add_co_u32_e32 v6, vcc, 0x25a000, v4
	v_readlane_b32 s37, v250, 1
	s_nop 0
	v_addc_co_u32_e32 v7, vcc, 0, v5, vcc
	v_add_co_u32_e32 v12, vcc, 0x264000, v4
	v_readlane_b32 s38, v250, 2
	s_nop 0
	v_addc_co_u32_e32 v13, vcc, 0, v5, vcc
	global_load_dwordx4 v[4:7], v[6:7], off nt
	s_nop 0
	global_load_dwordx4 v[12:15], v[12:13], off offset:3072 nt
	s_andn2_b64 vcc, exec, s[6:7]
	v_readlane_b32 s39, v250, 3
	v_readlane_b32 s42, v250, 6
	v_readlane_b32 s43, v250, 7
	s_cbranch_vccnz .LBB0_1682
	s_lshl_b32 s6, s0, 12
	s_ashr_i32 s7, s6, 31
	s_lshl_b64 s[6:7], s[6:7], 2
	s_add_u32 s6, s36, s6
	s_addc_u32 s7, s37, s7
	s_lshl_b32 s14, s8, 2
	s_add_u32 s6, s6, s14
	s_addc_u32 s7, s7, 0
	v_lshlrev_b32_e32 v103, 2, v72
	global_load_dwordx2 v[116:117], v103, s[6:7]
	global_load_dwordx2 v[118:119], v103, s[6:7] offset:32
	global_load_dwordx2 v[120:121], v103, s[6:7] offset:64
	global_load_dwordx2 v[122:123], v103, s[6:7] offset:96
	global_load_dwordx2 v[124:125], v103, s[6:7] offset:128
	global_load_dwordx2 v[126:127], v103, s[6:7] offset:160
	global_load_dwordx2 v[128:129], v103, s[6:7] offset:192
	global_load_dwordx2 v[130:131], v103, s[6:7] offset:224
	s_waitcnt vmcnt(0)
	v_pk_mul_f32 v[62:63], v[62:63], v[116:117] op_sel_hi:[1,0]
	v_pk_mul_f32 v[60:61], v[60:61], v[116:117] op_sel_hi:[1,0]
	v_pk_mul_f32 v[66:67], v[66:67], v[116:117] op_sel:[0,1]
	v_pk_mul_f32 v[64:65], v[64:65], v[116:117] op_sel:[0,1]
	v_pk_mul_f32 v[54:55], v[54:55], v[118:119] op_sel_hi:[1,0]
	v_pk_mul_f32 v[52:53], v[52:53], v[118:119] op_sel_hi:[1,0]
	v_pk_mul_f32 v[58:59], v[58:59], v[118:119] op_sel:[0,1]
	v_pk_mul_f32 v[56:57], v[56:57], v[118:119] op_sel:[0,1]
	v_pk_mul_f32 v[46:47], v[46:47], v[120:121] op_sel_hi:[1,0]
	v_pk_mul_f32 v[44:45], v[44:45], v[120:121] op_sel_hi:[1,0]
	v_pk_mul_f32 v[50:51], v[50:51], v[120:121] op_sel:[0,1]
	v_pk_mul_f32 v[48:49], v[48:49], v[120:121] op_sel:[0,1]
	v_pk_mul_f32 v[38:39], v[38:39], v[122:123] op_sel_hi:[1,0]
	v_pk_mul_f32 v[36:37], v[36:37], v[122:123] op_sel_hi:[1,0]
	v_pk_mul_f32 v[42:43], v[42:43], v[122:123] op_sel:[0,1]
	v_pk_mul_f32 v[40:41], v[40:41], v[122:123] op_sel:[0,1]
	v_pk_mul_f32 v[22:23], v[22:23], v[124:125] op_sel_hi:[1,0]
	v_pk_mul_f32 v[20:21], v[20:21], v[124:125] op_sel_hi:[1,0]
	v_pk_mul_f32 v[34:35], v[34:35], v[124:125] op_sel:[0,1]
	v_pk_mul_f32 v[32:33], v[32:33], v[124:125] op_sel:[0,1]
	v_pk_mul_f32 v[18:19], v[18:19], v[126:127] op_sel_hi:[1,0]
	v_pk_mul_f32 v[16:17], v[16:17], v[126:127] op_sel_hi:[1,0]
	v_pk_mul_f32 v[30:31], v[30:31], v[126:127] op_sel:[0,1]
	v_pk_mul_f32 v[28:29], v[28:29], v[126:127] op_sel:[0,1]
	v_pk_mul_f32 v[10:11], v[10:11], v[128:129] op_sel_hi:[1,0]
	v_pk_mul_f32 v[8:9], v[8:9], v[128:129] op_sel_hi:[1,0]
	v_pk_mul_f32 v[26:27], v[26:27], v[128:129] op_sel:[0,1]
	v_pk_mul_f32 v[24:25], v[24:25], v[128:129] op_sel:[0,1]
	v_pk_mul_f32 v[6:7], v[6:7], v[130:131] op_sel_hi:[1,0]
	v_pk_mul_f32 v[4:5], v[4:5], v[130:131] op_sel_hi:[1,0]
	v_pk_mul_f32 v[14:15], v[14:15], v[130:131] op_sel:[0,1]
	v_pk_mul_f32 v[12:13], v[12:13], v[130:131] op_sel:[0,1]

;     ...
;     const float* src = W + (size_t)(k0 + 2 * q) * N + n0 + 4 * r16;
;     f32x4 v[16];
; #pragma unroll
;     for (int j = 0; j < 16; ++j) v[j] = *(const f32x4*)(src + (size_t)(8 * (j >> 1) + (j & 1)) * N);
;     if (nscale) { const f32x4 ns = *(const f32x4*)(nscale + n0 + 4 * r16);
; #pragma unroll
;         for (int j = 0; j < 16; ++j) v[j] = v[j] * ns; }
;     if (kscale) {
; #pragma unroll
;         for (int i = 0; i < 8; ++i) { const f32x2 g = *(const f32x2*)(kscale + k0 + 8 * i + 2 * q); v[2 * i] = v[2 * i] * g[0]; v[2 * i + 1] = v[2 * i + 1] * g[1]; } }
; __device__ __forceinline__ void weights_pass(const Args& a, LAS unsigned char* scr, int gw, int NGW, int lane, int pass) {
;     ...
;         if (r < I_G) { transpose_item<2>(a.in[I_WGATE] + (size_t)l * DM * DFF, DM, DFF, (bf16_t*)(wl + WL_GU), a.in[I_GFFN] + l * DM, nullptr, 0, scr, r, lane); continue; } r -= I_G;
.LBB0_1684:
	s_andn2_b64 vcc, exec, s[6:7]
	s_cbranch_vccnz .LBB0_1688
	v_readlane_b32 s36, v250, 0
	v_readlane_b32 s38, v250, 2
	v_readlane_b32 s39, v250, 3
	s_add_u32 s6, s38, s3
	s_addc_u32 s7, s39, s2
	s_add_i32 s2, s21, 0xd600
	s_and_b32 s3, s2, 0xffff
	s_mul_i32 s3, s3, 0xbe83
	s_lshr_b32 s8, s3, 23
	s_mul_i32 s3, s8, 0xac
	s_sub_i32 s2, s2, s3
	s_and_b32 s3, s2, 0xffff
	s_lshl_b32 s2, s8, 6
	v_or_b32_e32 v4, s2, v72
	v_mul_u32_u24_e32 v4, 0x2b00, v4
	v_lshlrev_b32_e32 v4, 2, v4
	v_mov_b32_e32 v5, v2
	v_lshl_add_u64 v[4:5], s[6:7], 0, v[4:5]
	s_lshl_b32 s14, s3, 8
	v_lshl_add_u64 v[4:5], v[4:5], 0, s[14:15]
	v_lshlrev_b32_e32 v6, 2, v68
	v_mov_b32_e32 v7, v2
	v_lshl_add_u64 v[4:5], v[4:5], 0, v[6:7]
	s_mov_b32 s6, 0xa000
	v_add_co_u32_e32 v6, vcc, s6, v4
	s_mov_b32 s6, 0x56000
	s_nop 0
	v_addc_co_u32_e32 v7, vcc, 0, v5, vcc
	global_load_dwordx4 v[60:63], v[4:5], off nt
	global_load_dwordx4 v[64:67], v[6:7], off offset:3072 nt
	v_add_co_u32_e32 v6, vcc, s6, v4
	s_mov_b32 s6, 0x60000
	s_nop 0
	v_addc_co_u32_e32 v7, vcc, 0, v5, vcc
	v_add_co_u32_e32 v8, vcc, s6, v4
	s_mov_b32 s6, 0xac000
	s_nop 0
	v_addc_co_u32_e32 v9, vcc, 0, v5, vcc
	global_load_dwordx4 v[52:55], v[6:7], off nt
	global_load_dwordx4 v[56:59], v[8:9], off offset:3072 nt
	v_add_co_u32_e32 v6, vcc, s6, v4
	s_mov_b32 s6, 0xb6000
	s_nop 0
	v_addc_co_u32_e32 v7, vcc, 0, v5, vcc
	v_add_co_u32_e32 v8, vcc, s6, v4
	s_mov_b32 s6, 0x102000
	s_nop 0
	v_addc_co_u32_e32 v9, vcc, 0, v5, vcc
	global_load_dwordx4 v[44:47], v[6:7], off nt
	global_load_dwordx4 v[48:51], v[8:9], off offset:3072 nt
	v_add_co_u32_e32 v6, vcc, s6, v4
	s_mov_b32 s6, 0x10c000
	s_nop 0
	v_addc_co_u32_e32 v7, vcc, 0, v5, vcc
	v_add_co_u32_e32 v8, vcc, s6, v4
	s_mov_b32 s6, 0x158000
	s_nop 0
	v_addc_co_u32_e32 v9, vcc, 0, v5, vcc
	global_load_dwordx4 v[36:39], v[6:7], off nt
	global_load_dwordx4 v[40:43], v[8:9], off offset:3072 nt
	v_add_co_u32_e32 v6, vcc, s6, v4
	s_mov_b32 s6, 0x162000
	s_nop 0
	v_addc_co_u32_e32 v7, vcc, 0, v5, vcc
	v_add_co_u32_e32 v8, vcc, s6, v4
	s_mov_b32 s6, 0x1ae000
	s_nop 0
	v_addc_co_u32_e32 v9, vcc, 0, v5, vcc
	global_load_dwordx4 v[20:23], v[6:7], off nt
	global_load_dwordx4 v[32:35], v[8:9], off offset:3072 nt
	v_add_co_u32_e32 v6, vcc, s6, v4
	s_mov_b32 s6, 0x1b8000
	s_nop 0
	v_addc_co_u32_e32 v7, vcc, 0, v5, vcc
	v_add_co_u32_e32 v8, vcc, s6, v4
	s_mov_b32 s6, 0x204000
	s_nop 0
	v_addc_co_u32_e32 v9, vcc, 0, v5, vcc
	global_load_dwordx4 v[16:19], v[6:7], off nt
	global_load_dwordx4 v[28:31], v[8:9], off offset:3072 nt
	v_add_co_u32_e32 v6, vcc, s6, v4
	v_readlane_b32 s6, v253, 7
	s_nop 0
	v_addc_co_u32_e32 v7, vcc, 0, v5, vcc
	v_add_co_u32_e32 v12, vcc, 0x20e000, v4
	v_readlane_b32 s7, v253, 8
	s_nop 0
	v_addc_co_u32_e32 v13, vcc, 0, v5, vcc
	global_load_dwordx4 v[8:11], v[6:7], off nt
	global_load_dwordx4 v[24:27], v[12:13], off offset:3072 nt
	v_add_co_u32_e32 v6, vcc, 0x25a000, v4
	v_readlane_b32 s37, v250, 1
	s_nop 0
	v_addc_co_u32_e32 v7, vcc, 0, v5, vcc
	v_add_co_u32_e32 v12, vcc, 0x264000, v4
	v_readlane_b32 s40, v250, 4
	s_nop 0
	v_addc_co_u32_e32 v13, vcc, 0, v5, vcc
	global_load_dwordx4 v[4:7], v[6:7], off nt
	s_nop 0
	global_load_dwordx4 v[12:15], v[12:13], off offset:3072 nt
	s_andn2_b64 vcc, exec, s[6:7]
	v_readlane_b32 s41, v250, 5
	v_readlane_b32 s42, v250, 6
	v_readlane_b32 s43, v250, 7
	s_cbranch_vccnz .LBB0_1687
	s_lshl_b32 s6, s0, 12
	s_ashr_i32 s7, s6, 31
	s_lshl_b64 s[6:7], s[6:7], 2
	s_add_u32 s6, s36, s6
	s_addc_u32 s7, s37, s7
	s_lshl_b32 s8, s2, 2
	s_add_u32 s6, s6, s8
	s_addc_u32 s7, s7, 0
	v_lshlrev_b32_e32 v103, 2, v72
	global_load_dwordx2 v[116:117], v103, s[6:7]
	global_load_dwordx2 v[118:119], v103, s[6:7] offset:32
	global_load_dwordx2 v[120:121], v103, s[6:7] offset:64
	global_load_dwordx2 v[122:123], v103, s[6:7] offset:96
	global_load_dwordx2 v[124:125], v103, s[6:7] offset:128
	global_load_dwordx2 v[126:127], v103, s[6:7] offset:160
	global_load_dwordx2 v[128:129], v103, s[6:7] offset:192
	global_load_dwordx2 v[130:131], v103, s[6:7] offset:224
	s_waitcnt vmcnt(0)
	v_pk_mul_f32 v[62:63], v[62:63], v[116:117] op_sel_hi:[1,0]
	v_pk_mul_f32 v[60:61], v[60:61], v[116:117] op_sel_hi:[1,0]
	v_pk_mul_f32 v[66:67], v[66:67], v[116:117] op_sel:[0,1]
	v_pk_mul_f32 v[64:65], v[64:65], v[116:117] op_sel:[0,1]
	v_pk_mul_f32 v[54:55], v[54:55], v[118:119] op_sel_hi:[1,0]
	v_pk_mul_f32 v[52:53], v[52:53], v[118:119] op_sel_hi:[1,0]
	v_pk_mul_f32 v[58:59], v[58:59], v[118:119] op_sel:[0,1]
	v_pk_mul_f32 v[56:57], v[56:57], v[118:119] op_sel:[0,1]
	v_pk_mul_f32 v[46:47], v[46:47], v[120:121] op_sel_hi:[1,0]
	v_pk_mul_f32 v[44:45], v[44:45], v[120:121] op_sel_hi:[1,0]
	v_pk_mul_f32 v[50:51], v[50:51], v[120:121] op_sel:[0,1]
	v_pk_mul_f32 v[48:49], v[48:49], v[120:121] op_sel:[0,1]
	v_pk_mul_f32 v[38:39], v[38:39], v[122:123] op_sel_hi:[1,0]
	v_pk_mul_f32 v[36:37], v[36:37], v[122:123] op_sel_hi:[1,0]
	v_pk_mul_f32 v[42:43], v[42:43], v[122:123] op_sel:[0,1]
	v_pk_mul_f32 v[40:41], v[40:41], v[122:123] op_sel:[0,1]
	v_pk_mul_f32 v[22:23], v[22:23], v[124:125] op_sel_hi:[1,0]
	v_pk_mul_f32 v[20:21], v[20:21], v[124:125] op_sel_hi:[1,0]
	v_pk_mul_f32 v[34:35], v[34:35], v[124:125] op_sel:[0,1]
	v_pk_mul_f32 v[32:33], v[32:33], v[124:125] op_sel:[0,1]
	v_pk_mul_f32 v[18:19], v[18:19], v[126:127] op_sel_hi:[1,0]
	v_pk_mul_f32 v[16:17], v[16:17], v[126:127] op_sel_hi:[1,0]
	v_pk_mul_f32 v[30:31], v[30:31], v[126:127] op_sel:[0,1]
	v_pk_mul_f32 v[28:29], v[28:29], v[126:127] op_sel:[0,1]
	v_pk_mul_f32 v[10:11], v[10:11], v[128:129] op_sel_hi:[1,0]
	v_pk_mul_f32 v[8:9], v[8:9], v[128:129] op_sel_hi:[1,0]
	v_pk_mul_f32 v[26:27], v[26:27], v[128:129] op_sel:[0,1]
	v_pk_mul_f32 v[24:25], v[24:25], v[128:129] op_sel:[0,1]
	v_pk_mul_f32 v[6:7], v[6:7], v[130:131] op_sel_hi:[1,0]
	v_pk_mul_f32 v[4:5], v[4:5], v[130:131] op_sel_hi:[1,0]
	v_pk_mul_f32 v[14:15], v[14:15], v[130:131] op_sel:[0,1]
	v_pk_mul_f32 v[12:13], v[12:13], v[130:131] op_sel:[0,1]

;     ...
;     const float* src = W + (size_t)(k0 + 2 * q) * N + n0 + 4 * r16;
;     f32x4 v[16];
; #pragma unroll
;     for (int j = 0; j < 16; ++j) v[j] = *(const f32x4*)(src + (size_t)(8 * (j >> 1) + (j & 1)) * N);
;     if (nscale) { const f32x4 ns = *(const f32x4*)(nscale + n0 + 4 * r16);
; #pragma unroll
;         for (int j = 0; j < 16; ++j) v[j] = v[j] * ns; }
;     if (kscale) {
; #pragma unroll
;         for (int i = 0; i < 8; ++i) { const f32x2 g = *(const f32x2*)(kscale + k0 + 8 * i + 2 * q); v[2 * i] = v[2 * i] * g[0]; v[2 * i + 1] = v[2 * i + 1] * g[1]; } }
; __device__ __forceinline__ void weights_pass(const Args& a, LAS unsigned char* scr, int gw, int NGW, int lane, int pass) {
;     ...
;         if (r < I_QM) { transpose_item<1>(a.in[I_WVM] + (size_t)l * DM * MW, DM, MW, (bf16_t*)(ws + WS_WKV) + (size_t)l * 1024 * DM, a.in[I_GMEM] + l * DM, nullptr, 512, scr, r, lane); continue; } r -= I_QM;
.LBB0_1692:
	s_andn2_b64 vcc, exec, s[6:7]
	s_cbranch_vccnz .LBB0_1696
	v_readlane_b32 s36, v250, 46
	s_lshl_b64 s[6:7], s[0:1], 23
	v_readlane_b32 s44, v250, 54
	v_readlane_b32 s45, v250, 55
	s_add_u32 s8, s44, s6
	s_mul_i32 s2, s0, 0xfffaa800
	s_addc_u32 s9, s45, s7
	s_add_i32 s2, s11, s2
	s_addk_i32 s2, 0xe000
	s_and_b32 s2, s2, 0x7ffc0
	v_or_b32_e32 v4, s2, v72
	s_and_b32 s3, s17, 0x1c0
	v_lshlrev_b32_e32 v4, 11, v4
	v_mov_b32_e32 v5, v2
	v_lshl_add_u64 v[4:5], s[8:9], 0, v[4:5]
	s_lshl_b32 s14, s3, 2
	v_lshl_add_u64 v[4:5], v[4:5], 0, s[14:15]
	v_lshlrev_b32_e32 v6, 2, v68
	v_mov_b32_e32 v7, v2
	v_lshl_add_u64 v[4:5], v[4:5], 0, v[6:7]
	s_movk_i32 s8, 0x4000
	v_add_co_u32_e32 v6, vcc, s8, v4
	s_mov_b32 s8, 0x8000
	s_nop 0
	v_addc_co_u32_e32 v7, vcc, 0, v5, vcc
	global_load_dwordx4 v[60:63], v[4:5], off nt
	global_load_dwordx4 v[64:67], v[4:5], off offset:2048 nt
	global_load_dwordx4 v[52:55], v[6:7], off nt
	global_load_dwordx4 v[56:59], v[6:7], off offset:2048 nt
	v_add_co_u32_e32 v6, vcc, s8, v4
	s_mov_b32 s8, 0x10000
	s_nop 0
	v_addc_co_u32_e32 v7, vcc, 0, v5, vcc
	global_load_dwordx4 v[44:47], v[6:7], off nt
	global_load_dwordx4 v[48:51], v[6:7], off offset:2048 nt
	v_add_co_u32_e32 v6, vcc, 0xc000, v4
	v_readlane_b32 s38, v250, 48
	s_nop 0
	v_addc_co_u32_e32 v7, vcc, 0, v5, vcc
	global_load_dwordx4 v[36:39], v[6:7], off nt
	global_load_dwordx4 v[40:43], v[6:7], off offset:2048 nt
	v_add_co_u32_e32 v6, vcc, s8, v4
	s_mov_b32 s8, 0x14000
	s_nop 0
	v_addc_co_u32_e32 v7, vcc, 0, v5, vcc
	global_load_dwordx4 v[28:31], v[6:7], off nt
	global_load_dwordx4 v[32:35], v[6:7], off offset:2048 nt
	v_add_co_u32_e32 v6, vcc, s8, v4
	v_readlane_b32 s8, v253, 9
	s_nop 0
	v_addc_co_u32_e32 v7, vcc, 0, v5, vcc
	global_load_dwordx4 v[20:23], v[6:7], off nt
	global_load_dwordx4 v[24:27], v[6:7], off offset:2048 nt
	v_add_co_u32_e32 v6, vcc, 0x18000, v4
	v_readlane_b32 s9, v253, 10
	s_nop 0
	v_addc_co_u32_e32 v7, vcc, 0, v5, vcc
	v_add_co_u32_e32 v8, vcc, 0x1c000, v4
	global_load_dwordx4 v[12:15], v[6:7], off nt
	global_load_dwordx4 v[16:19], v[6:7], off offset:2048 nt
	v_addc_co_u32_e32 v9, vcc, 0, v5, vcc
	global_load_dwordx4 v[4:7], v[8:9], off nt
	s_nop 0
	global_load_dwordx4 v[8:11], v[8:9], off offset:2048 nt
	v_readlane_b32 s39, v250, 49
	s_andn2_b64 vcc, exec, s[8:9]
	v_readlane_b32 s37, v250, 47
	v_readlane_b32 s40, v250, 50
	v_readlane_b32 s41, v250, 51
	v_readlane_b32 s42, v250, 52
	v_readlane_b32 s43, v250, 53
	v_readlane_b32 s46, v250, 56
	v_readlane_b32 s47, v250, 57
	v_readlane_b32 s48, v250, 58
	v_readlane_b32 s49, v250, 59
	v_readlane_b32 s50, v250, 60
	v_readlane_b32 s51, v250, 61
	s_cbranch_vccnz .LBB0_1695
	s_lshl_b32 s8, s0, 12
	s_ashr_i32 s9, s8, 31
	s_lshl_b64 s[8:9], s[8:9], 2
	s_add_u32 s8, s38, s8
	s_addc_u32 s9, s39, s9
	s_lshl_b32 s14, s2, 2
	s_add_u32 s8, s8, s14
	s_addc_u32 s9, s9, 0
	v_lshlrev_b32_e32 v103, 2, v72
	global_load_dwordx2 v[116:117], v103, s[8:9]
	global_load_dwordx2 v[118:119], v103, s[8:9] offset:32
	global_load_dwordx2 v[120:121], v103, s[8:9] offset:64
	global_load_dwordx2 v[122:123], v103, s[8:9] offset:96
	global_load_dwordx2 v[124:125], v103, s[8:9] offset:128
	global_load_dwordx2 v[126:127], v103, s[8:9] offset:160
	global_load_dwordx2 v[128:129], v103, s[8:9] offset:192
	global_load_dwordx2 v[130:131], v103, s[8:9] offset:224
	s_waitcnt vmcnt(0)
	v_pk_mul_f32 v[62:63], v[62:63], v[116:117] op_sel_hi:[1,0]
	v_pk_mul_f32 v[60:61], v[60:61], v[116:117] op_sel_hi:[1,0]
	v_pk_mul_f32 v[66:67], v[66:67], v[116:117] op_sel:[0,1]
	v_pk_mul_f32 v[64:65], v[64:65], v[116:117] op_sel:[0,1]
	v_pk_mul_f32 v[54:55], v[54:55], v[118:119] op_sel_hi:[1,0]
	v_pk_mul_f32 v[52:53], v[52:53], v[118:119] op_sel_hi:[1,0]
	v_pk_mul_f32 v[58:59], v[58:59], v[118:119] op_sel:[0,1]
	v_pk_mul_f32 v[56:57], v[56:57], v[118:119] op_sel:[0,1]
	v_pk_mul_f32 v[46:47], v[46:47], v[120:121] op_sel_hi:[1,0]
	v_pk_mul_f32 v[44:45], v[44:45], v[120:121] op_sel_hi:[1,0]
	v_pk_mul_f32 v[50:51], v[50:51], v[120:121] op_sel:[0,1]
	v_pk_mul_f32 v[48:49], v[48:49], v[120:121] op_sel:[0,1]
	v_pk_mul_f32 v[38:39], v[38:39], v[122:123] op_sel_hi:[1,0]
	v_pk_mul_f32 v[36:37], v[36:37], v[122:123] op_sel_hi:[1,0]
	v_pk_mul_f32 v[42:43], v[42:43], v[122:123] op_sel:[0,1]
	v_pk_mul_f32 v[40:41], v[40:41], v[122:123] op_sel:[0,1]
	v_pk_mul_f32 v[30:31], v[30:31], v[124:125] op_sel_hi:[1,0]
	v_pk_mul_f32 v[28:29], v[28:29], v[124:125] op_sel_hi:[1,0]
	v_pk_mul_f32 v[34:35], v[34:35], v[124:125] op_sel:[0,1]
	v_pk_mul_f32 v[32:33], v[32:33], v[124:125] op_sel:[0,1]
	v_pk_mul_f32 v[22:23], v[22:23], v[126:127] op_sel_hi:[1,0]
	v_pk_mul_f32 v[20:21], v[20:21], v[126:127] op_sel_hi:[1,0]
	v_pk_mul_f32 v[26:27], v[26:27], v[126:127] op_sel:[0,1]
	v_pk_mul_f32 v[24:25], v[24:25], v[126:127] op_sel:[0,1]
	v_pk_mul_f32 v[14:15], v[14:15], v[128:129] op_sel_hi:[1,0]
	v_pk_mul_f32 v[12:13], v[12:13], v[128:129] op_sel_hi:[1,0]
	v_pk_mul_f32 v[18:19], v[18:19], v[128:129] op_sel:[0,1]
	v_pk_mul_f32 v[16:17], v[16:17], v[128:129] op_sel:[0,1]
	v_pk_mul_f32 v[6:7], v[6:7], v[130:131] op_sel_hi:[1,0]
	v_pk_mul_f32 v[4:5], v[4:5], v[130:131] op_sel_hi:[1,0]
	v_pk_mul_f32 v[10:11], v[10:11], v[130:131] op_sel:[0,1]
	v_pk_mul_f32 v[8:9], v[8:9], v[130:131] op_sel:[0,1]

;     ...
;     const float* src = W + (size_t)(k0 + 2 * q) * N + n0 + 4 * r16;
;     f32x4 v[16];
; #pragma unroll
;     for (int j = 0; j < 16; ++j) v[j] = *(const f32x4*)(src + (size_t)(8 * (j >> 1) + (j & 1)) * N);
;     if (nscale) { const f32x4 ns = *(const f32x4*)(nscale + n0 + 4 * r16);
; #pragma unroll
;         for (int j = 0; j < 16; ++j) v[j] = v[j] * ns; }
;     if (kscale) {
; #pragma unroll
;         for (int i = 0; i < 8; ++i) { const f32x2 g = *(const f32x2*)(kscale + k0 + 8 * i + 2 * q); v[2 * i] = v[2 * i] * g[0]; v[2 * i + 1] = v[2 * i + 1] * g[1]; } }
; __device__ __forceinline__ void weights_pass(const Args& a, LAS unsigned char* scr, int gw, int NGW, int lane, int pass) {
;     ...
;         if (r < I_QM) { transpose_item<1>(a.in[I_WKM] + (size_t)l * DM * MW, DM, MW, (bf16_t*)(ws + WS_WKV) + (size_t)l * 1024 * DM, a.in[I_GMEM] + l * DM, nullptr, 0, scr, r, lane); continue; } r -= I_QM;
.LBB0_1697:
	s_andn2_b64 vcc, exec, s[6:7]
	s_cbranch_vccnz .LBB0_1701
	v_readlane_b32 s36, v250, 46
	s_lshl_b64 s[6:7], s[0:1], 23
	v_readlane_b32 s42, v250, 52
	v_readlane_b32 s43, v250, 53
	s_add_u32 s8, s42, s6
	s_mul_i32 s2, s0, 0xfffaa800
	s_addc_u32 s9, s43, s7
	s_add_i32 s2, s11, s2
	s_addk_i32 s2, 0xf000
	s_and_b32 s3, s2, 0x7ffc0
	s_mul_i32 s2, s0, 0xffd54000
	s_add_i32 s2, s17, s2
	v_or_b32_e32 v4, s3, v72
	s_and_b32 s14, s2, 0x1c0
	v_lshlrev_b32_e32 v4, 11, v4
	v_mov_b32_e32 v5, v2
	v_lshl_add_u64 v[4:5], s[8:9], 0, v[4:5]
	s_lshl_b32 s14, s14, 2
	v_lshl_add_u64 v[4:5], v[4:5], 0, s[14:15]
	v_lshlrev_b32_e32 v6, 2, v68
	v_mov_b32_e32 v7, v2
	v_lshl_add_u64 v[4:5], v[4:5], 0, v[6:7]
	s_movk_i32 s8, 0x4000
	v_add_co_u32_e32 v6, vcc, s8, v4
	s_mov_b32 s8, 0x8000
	s_nop 0
	v_addc_co_u32_e32 v7, vcc, 0, v5, vcc
	global_load_dwordx4 v[60:63], v[4:5], off nt
	global_load_dwordx4 v[64:67], v[4:5], off offset:2048 nt
	global_load_dwordx4 v[52:55], v[6:7], off nt
	global_load_dwordx4 v[56:59], v[6:7], off offset:2048 nt
	v_add_co_u32_e32 v6, vcc, s8, v4
	s_mov_b32 s8, 0x10000
	s_nop 0
	v_addc_co_u32_e32 v7, vcc, 0, v5, vcc
	global_load_dwordx4 v[44:47], v[6:7], off nt
	global_load_dwordx4 v[48:51], v[6:7], off offset:2048 nt
	v_add_co_u32_e32 v6, vcc, 0xc000, v4
	v_readlane_b32 s38, v250, 48
	s_nop 0
	v_addc_co_u32_e32 v7, vcc, 0, v5, vcc
	global_load_dwordx4 v[36:39], v[6:7], off nt
	global_load_dwordx4 v[40:43], v[6:7], off offset:2048 nt
	v_add_co_u32_e32 v6, vcc, s8, v4
	s_mov_b32 s8, 0x14000
	s_nop 0
	v_addc_co_u32_e32 v7, vcc, 0, v5, vcc
	global_load_dwordx4 v[28:31], v[6:7], off nt
	global_load_dwordx4 v[32:35], v[6:7], off offset:2048 nt
	v_add_co_u32_e32 v6, vcc, s8, v4
	v_readlane_b32 s8, v253, 9
	s_nop 0
	v_addc_co_u32_e32 v7, vcc, 0, v5, vcc
	global_load_dwordx4 v[20:23], v[6:7], off nt
	global_load_dwordx4 v[24:27], v[6:7], off offset:2048 nt
	v_add_co_u32_e32 v6, vcc, 0x18000, v4
	v_readlane_b32 s9, v253, 10
	s_nop 0
	v_addc_co_u32_e32 v7, vcc, 0, v5, vcc
	v_add_co_u32_e32 v8, vcc, 0x1c000, v4
	global_load_dwordx4 v[12:15], v[6:7], off nt
	global_load_dwordx4 v[16:19], v[6:7], off offset:2048 nt
	v_addc_co_u32_e32 v9, vcc, 0, v5, vcc
	global_load_dwordx4 v[4:7], v[8:9], off nt
	s_nop 0
	global_load_dwordx4 v[8:11], v[8:9], off offset:2048 nt
	v_readlane_b32 s39, v250, 49
	s_andn2_b64 vcc, exec, s[8:9]
	v_readlane_b32 s37, v250, 47
	v_readlane_b32 s40, v250, 50
	v_readlane_b32 s41, v250, 51
	v_readlane_b32 s44, v250, 54
	v_readlane_b32 s45, v250, 55
	v_readlane_b32 s46, v250, 56
	v_readlane_b32 s47, v250, 57
	v_readlane_b32 s48, v250, 58
	v_readlane_b32 s49, v250, 59
	v_readlane_b32 s50, v250, 60
	v_readlane_b32 s51, v250, 61
	s_cbranch_vccnz .LBB0_1700
	s_lshl_b32 s8, s0, 12
	s_ashr_i32 s9, s8, 31
	s_lshl_b64 s[8:9], s[8:9], 2
	s_add_u32 s8, s38, s8
	s_addc_u32 s9, s39, s9
	s_lshl_b32 s14, s3, 2
	s_add_u32 s8, s8, s14
	s_addc_u32 s9, s9, 0
	v_lshlrev_b32_e32 v103, 2, v72
	global_load_dwordx2 v[116:117], v103, s[8:9]
	global_load_dwordx2 v[118:119], v103, s[8:9] offset:32
	global_load_dwordx2 v[120:121], v103, s[8:9] offset:64
	global_load_dwordx2 v[122:123], v103, s[8:9] offset:96
	global_load_dwordx2 v[124:125], v103, s[8:9] offset:128
	global_load_dwordx2 v[126:127], v103, s[8:9] offset:160
	global_load_dwordx2 v[128:129], v103, s[8:9] offset:192
	global_load_dwordx2 v[130:131], v103, s[8:9] offset:224
	s_waitcnt vmcnt(0)
	v_pk_mul_f32 v[62:63], v[62:63], v[116:117] op_sel_hi:[1,0]
	v_pk_mul_f32 v[60:61], v[60:61], v[116:117] op_sel_hi:[1,0]
	v_pk_mul_f32 v[66:67], v[66:67], v[116:117] op_sel:[0,1]
	v_pk_mul_f32 v[64:65], v[64:65], v[116:117] op_sel:[0,1]
	v_pk_mul_f32 v[54:55], v[54:55], v[118:119] op_sel_hi:[1,0]
	v_pk_mul_f32 v[52:53], v[52:53], v[118:119] op_sel_hi:[1,0]
	v_pk_mul_f32 v[58:59], v[58:59], v[118:119] op_sel:[0,1]
	v_pk_mul_f32 v[56:57], v[56:57], v[118:119] op_sel:[0,1]
	v_pk_mul_f32 v[46:47], v[46:47], v[120:121] op_sel_hi:[1,0]
	v_pk_mul_f32 v[44:45], v[44:45], v[120:121] op_sel_hi:[1,0]
	v_pk_mul_f32 v[50:51], v[50:51], v[120:121] op_sel:[0,1]
	v_pk_mul_f32 v[48:49], v[48:49], v[120:121] op_sel:[0,1]
	v_pk_mul_f32 v[38:39], v[38:39], v[122:123] op_sel_hi:[1,0]
	v_pk_mul_f32 v[36:37], v[36:37], v[122:123] op_sel_hi:[1,0]
	v_pk_mul_f32 v[42:43], v[42:43], v[122:123] op_sel:[0,1]
	v_pk_mul_f32 v[40:41], v[40:41], v[122:123] op_sel:[0,1]
	v_pk_mul_f32 v[30:31], v[30:31], v[124:125] op_sel_hi:[1,0]
	v_pk_mul_f32 v[28:29], v[28:29], v[124:125] op_sel_hi:[1,0]
	v_pk_mul_f32 v[34:35], v[34:35], v[124:125] op_sel:[0,1]
	v_pk_mul_f32 v[32:33], v[32:33], v[124:125] op_sel:[0,1]
	v_pk_mul_f32 v[22:23], v[22:23], v[126:127] op_sel_hi:[1,0]
	v_pk_mul_f32 v[20:21], v[20:21], v[126:127] op_sel_hi:[1,0]
	v_pk_mul_f32 v[26:27], v[26:27], v[126:127] op_sel:[0,1]
	v_pk_mul_f32 v[24:25], v[24:25], v[126:127] op_sel:[0,1]
	v_pk_mul_f32 v[14:15], v[14:15], v[128:129] op_sel_hi:[1,0]
	v_pk_mul_f32 v[12:13], v[12:13], v[128:129] op_sel_hi:[1,0]
	v_pk_mul_f32 v[18:19], v[18:19], v[128:129] op_sel:[0,1]
	v_pk_mul_f32 v[16:17], v[16:17], v[128:129] op_sel:[0,1]
	v_pk_mul_f32 v[6:7], v[6:7], v[130:131] op_sel_hi:[1,0]
	v_pk_mul_f32 v[4:5], v[4:5], v[130:131] op_sel_hi:[1,0]
	v_pk_mul_f32 v[10:11], v[10:11], v[130:131] op_sel:[0,1]
	v_pk_mul_f32 v[8:9], v[8:9], v[130:131] op_sel:[0,1]

;     const int nblk = N / 64, kb = item / nblk, nb = item % nblk, k0 = 64 * kb, n0 = 64 * nb;
;     const int r16 = lane & 15, q = lane >> 4;
;     const float* src = W + (size_t)(k0 + 2 * q) * N + n0 + 4 * r16;
;     f32x4 v[16];
; #pragma unroll
;     for (int j = 0; j < 16; ++j) v[j] = *(const f32x4*)(src + (size_t)(8 * (j >> 1) + (j & 1)) * N);
;     if (nscale) { const f32x4 ns = *(const f32x4*)(nscale + n0 + 4 * r16);
; #pragma unroll
;         for (int j = 0; j < 16; ++j) v[j] = v[j] * ns; }
;     if (kscale) {
; #pragma unroll
;         for (int i = 0; i < 8; ++i) { const f32x2 g = *(const f32x2*)(kscale + k0 + 8 * i + 2 * q); v[2 * i] = v[2 * i] * g[0]; v[2 * i + 1] = v[2 * i + 1] * g[1]; } }
; __device__ __forceinline__ void weights_pass(const Args& a, LAS unsigned char* scr, int gw, int NGW, int lane, int pass) {
;     ...
;         if (r < I_QM) { transpose_item<0>(a.in[I_WQM] + (size_t)l * DM * MW, DM, MW, (bf16_t*)(wl + WL_Q), a.in[I_GCROSS] + l * DM, nullptr, 0, scr, r, lane); continue; } r -= I_QM;
;         if (r < I_QM) { transpose_item<1>(a.in[I_WKM] + (size_t)l * DM * MW, DM, MW, (bf16_t*)(ws + WS_WKV) + (size_t)l * 1024 * DM, a.in[I_GMEM] + l * DM, nullptr, 0, scr, r, lane); continue; } r -= I_QM;
;         if (r < I_QM) { transpose_item<1>(a.in[I_WVM] + (size_t)l * DM * MW, DM, MW, (bf16_t*)(ws + WS_WKV) + (size_t)l * 1024 * DM, a.in[I_GMEM] + l * DM, nullptr, 512, scr, r, lane); continue; } r -= I_QM;
.LBB0_1702:
	s_andn2_b64 vcc, exec, s[6:7]
	s_cbranch_vccnz .LBB0_1706
	v_readlane_b32 s36, v250, 46
	s_lshl_b64 s[2:3], s[0:1], 23
	v_readlane_b32 s40, v250, 50
	v_readlane_b32 s41, v250, 51
	s_add_u32 s6, s40, s2
	s_mul_i32 s2, s0, 0xfffaa800
	s_addc_u32 s7, s41, s3
	s_add_i32 s2, s11, s2
	s_and_b32 s2, s2, 0x7ffc0
	s_lshl_b32 s3, s21, 6
	v_or_b32_e32 v4, s2, v72
	s_and_b32 s3, s3, 0x1c0
	v_lshlrev_b32_e32 v4, 11, v4
	v_mov_b32_e32 v5, v2
	v_lshl_add_u64 v[4:5], s[6:7], 0, v[4:5]
	s_lshl_b32 s14, s3, 2
	v_lshl_add_u64 v[4:5], v[4:5], 0, s[14:15]
	v_lshlrev_b32_e32 v6, 2, v68
	v_mov_b32_e32 v7, v2
	v_lshl_add_u64 v[4:5], v[4:5], 0, v[6:7]
	s_movk_i32 s6, 0x4000
	v_add_co_u32_e32 v6, vcc, s6, v4
	s_mov_b32 s6, 0x8000
	s_nop 0
	v_addc_co_u32_e32 v7, vcc, 0, v5, vcc
	global_load_dwordx4 v[60:63], v[4:5], off nt
	global_load_dwordx4 v[64:67], v[4:5], off offset:2048 nt
	global_load_dwordx4 v[52:55], v[6:7], off nt
	global_load_dwordx4 v[56:59], v[6:7], off offset:2048 nt
	v_add_co_u32_e32 v6, vcc, s6, v4
	s_mov_b32 s6, 0x10000
	s_nop 0
	v_addc_co_u32_e32 v7, vcc, 0, v5, vcc
	global_load_dwordx4 v[44:47], v[6:7], off nt
	global_load_dwordx4 v[48:51], v[6:7], off offset:2048 nt
	v_add_co_u32_e32 v6, vcc, 0xc000, v4
	v_readlane_b32 s37, v250, 47
	s_nop 0
	v_addc_co_u32_e32 v7, vcc, 0, v5, vcc
	global_load_dwordx4 v[36:39], v[6:7], off nt
	global_load_dwordx4 v[40:43], v[6:7], off offset:2048 nt
	v_add_co_u32_e32 v6, vcc, s6, v4
	s_mov_b32 s6, 0x14000
	s_nop 0
	v_addc_co_u32_e32 v7, vcc, 0, v5, vcc
	global_load_dwordx4 v[28:31], v[6:7], off nt
	global_load_dwordx4 v[32:35], v[6:7], off offset:2048 nt
	v_add_co_u32_e32 v6, vcc, s6, v4
	v_readlane_b32 s6, v253, 11
	s_nop 0
	v_addc_co_u32_e32 v7, vcc, 0, v5, vcc
	global_load_dwordx4 v[20:23], v[6:7], off nt
	global_load_dwordx4 v[24:27], v[6:7], off offset:2048 nt
	v_add_co_u32_e32 v6, vcc, 0x18000, v4
	v_readlane_b32 s7, v253, 12
	s_nop 0
	v_addc_co_u32_e32 v7, vcc, 0, v5, vcc
	v_add_co_u32_e32 v8, vcc, 0x1c000, v4
	global_load_dwordx4 v[12:15], v[6:7], off nt
	global_load_dwordx4 v[16:19], v[6:7], off offset:2048 nt
	v_addc_co_u32_e32 v9, vcc, 0, v5, vcc
	global_load_dwordx4 v[4:7], v[8:9], off nt
	s_nop 0
	global_load_dwordx4 v[8:11], v[8:9], off offset:2048 nt
	s_andn2_b64 vcc, exec, s[6:7]
	v_readlane_b32 s38, v250, 48
	v_readlane_b32 s39, v250, 49
	v_readlane_b32 s42, v250, 52
	v_readlane_b32 s43, v250, 53
	v_readlane_b32 s44, v250, 54
	v_readlane_b32 s45, v250, 55
	v_readlane_b32 s46, v250, 56
	v_readlane_b32 s47, v250, 57
	v_readlane_b32 s48, v250, 58
	v_readlane_b32 s49, v250, 59
	v_readlane_b32 s50, v250, 60
	v_readlane_b32 s51, v250, 61
	s_cbranch_vccnz .LBB0_1705
	s_lshl_b32 s6, s0, 12
	s_ashr_i32 s7, s6, 31
	s_lshl_b64 s[6:7], s[6:7], 2
	s_add_u32 s6, s36, s6
	s_addc_u32 s7, s37, s7
	s_lshl_b32 s8, s2, 2
	s_add_u32 s6, s6, s8
	s_addc_u32 s7, s7, 0
	v_lshlrev_b32_e32 v103, 2, v72
	global_load_dwordx2 v[116:117], v103, s[6:7]
	global_load_dwordx2 v[118:119], v103, s[6:7] offset:32
	global_load_dwordx2 v[120:121], v103, s[6:7] offset:64
	global_load_dwordx2 v[122:123], v103, s[6:7] offset:96
	global_load_dwordx2 v[124:125], v103, s[6:7] offset:128
	global_load_dwordx2 v[126:127], v103, s[6:7] offset:160
	global_load_dwordx2 v[128:129], v103, s[6:7] offset:192
	global_load_dwordx2 v[130:131], v103, s[6:7] offset:224
	s_waitcnt vmcnt(0)
	v_pk_mul_f32 v[62:63], v[62:63], v[116:117] op_sel_hi:[1,0]
	v_pk_mul_f32 v[60:61], v[60:61], v[116:117] op_sel_hi:[1,0]
	v_pk_mul_f32 v[66:67], v[66:67], v[116:117] op_sel:[0,1]
	v_pk_mul_f32 v[64:65], v[64:65], v[116:117] op_sel:[0,1]
	v_pk_mul_f32 v[54:55], v[54:55], v[118:119] op_sel_hi:[1,0]
	v_pk_mul_f32 v[52:53], v[52:53], v[118:119] op_sel_hi:[1,0]
	v_pk_mul_f32 v[58:59], v[58:59], v[118:119] op_sel:[0,1]
	v_pk_mul_f32 v[56:57], v[56:57], v[118:119] op_sel:[0,1]
	v_pk_mul_f32 v[46:47], v[46:47], v[120:121] op_sel_hi:[1,0]
	v_pk_mul_f32 v[44:45], v[44:45], v[120:121] op_sel_hi:[1,0]
	v_pk_mul_f32 v[50:51], v[50:51], v[120:121] op_sel:[0,1]
	v_pk_mul_f32 v[48:49], v[48:49], v[120:121] op_sel:[0,1]
	v_pk_mul_f32 v[38:39], v[38:39], v[122:123] op_sel_hi:[1,0]
	v_pk_mul_f32 v[36:37], v[36:37], v[122:123] op_sel_hi:[1,0]
	v_pk_mul_f32 v[42:43], v[42:43], v[122:123] op_sel:[0,1]
	v_pk_mul_f32 v[40:41], v[40:41], v[122:123] op_sel:[0,1]
	v_pk_mul_f32 v[30:31], v[30:31], v[124:125] op_sel_hi:[1,0]
	v_pk_mul_f32 v[28:29], v[28:29], v[124:125] op_sel_hi:[1,0]
	v_pk_mul_f32 v[34:35], v[34:35], v[124:125] op_sel:[0,1]
	v_pk_mul_f32 v[32:33], v[32:33], v[124:125] op_sel:[0,1]
	v_pk_mul_f32 v[22:23], v[22:23], v[126:127] op_sel_hi:[1,0]
	v_pk_mul_f32 v[20:21], v[20:21], v[126:127] op_sel_hi:[1,0]
	v_pk_mul_f32 v[26:27], v[26:27], v[126:127] op_sel:[0,1]
	v_pk_mul_f32 v[24:25], v[24:25], v[126:127] op_sel:[0,1]
	v_pk_mul_f32 v[14:15], v[14:15], v[128:129] op_sel_hi:[1,0]
	v_pk_mul_f32 v[12:13], v[12:13], v[128:129] op_sel_hi:[1,0]
	v_pk_mul_f32 v[18:19], v[18:19], v[128:129] op_sel:[0,1]
	v_pk_mul_f32 v[16:17], v[16:17], v[128:129] op_sel:[0,1]
	v_pk_mul_f32 v[6:7], v[6:7], v[130:131] op_sel_hi:[1,0]
	v_pk_mul_f32 v[4:5], v[4:5], v[130:131] op_sel_hi:[1,0]
	v_pk_mul_f32 v[10:11], v[10:11], v[130:131] op_sel:[0,1]
	v_pk_mul_f32 v[8:9], v[8:9], v[130:131] op_sel:[0,1]

;     const int nblk = N / 64, kb = item / nblk, nb = item % nblk, k0 = 64 * kb, n0 = 64 * nb;
;     const int r16 = lane & 15, q = lane >> 4;
;     const float* src = W + (size_t)(k0 + 2 * q) * N + n0 + 4 * r16;
;     f32x4 v[16];
; #pragma unroll
;     for (int j = 0; j < 16; ++j) v[j] = *(const f32x4*)(src + (size_t)(8 * (j >> 1) + (j & 1)) * N);
;     if (nscale) { const f32x4 ns = *(const f32x4*)(nscale + n0 + 4 * r16);
; #pragma unroll
;         for (int j = 0; j < 16; ++j) v[j] = v[j] * ns; }
;     if (kscale) {
; #pragma unroll
;         for (int i = 0; i < 8; ++i) { const f32x2 g = *(const f32x2*)(kscale + k0 + 8 * i + 2 * q); v[2 * i] = v[2 * i] * g[0]; v[2 * i + 1] = v[2 * i + 1] * g[1]; } }
; __device__ __forceinline__ void weights_pass(const Args& a, LAS unsigned char* scr, int gw, int NGW, int lane, int pass) {
;     ...
;         if (r < I_IN) { transpose_item<1>(a.in[I_WIN] + (size_t)l * DM * INW, DM, INW, (bf16_t*)(wl + WL_IN), a.in[I_GMIX] + l * DM, nullptr, 0, scr, r, lane); continue; } r -= I_IN;
.LBB0_1713:
	s_andn2_b64 vcc, exec, s[6:7]
	s_cbranch_vccnz .LBB0_1667
	s_mul_i32 s2, s0, 0x4800000
	s_mul_hi_i32 s3, s0, 0x4800000
	s_add_u32 s2, s62, s2
	s_mul_hi_i32 s6, s21, 0x38e38e39
	s_addc_u32 s3, s63, s3
	s_lshr_b32 s7, s6, 31
	s_ashr_i32 s6, s6, 4
	s_add_i32 s6, s6, s7
	s_mul_i32 s1, s0, 0xab00
	s_mul_i32 s7, s6, 0xffffffb8
	s_sub_i32 s1, s7, s1
	s_add_i32 s1, s10, s1
	s_lshl_b32 s8, s6, 6
	s_lshl_b32 s6, s1, 6
	v_or_b32_e32 v4, s8, v72
	s_movk_i32 s1, 0x1200
	v_mul_lo_u32 v4, v4, s1
	v_ashrrev_i32_e32 v5, 31, v4
	v_lshl_add_u64 v[4:5], v[4:5], 2, s[2:3]
	s_ashr_i32 s7, s6, 31
	v_lshl_add_u64 v[4:5], s[6:7], 2, v[4:5]
	v_lshlrev_b32_e32 v6, 2, v68
	v_mov_b32_e32 v7, v2
	v_lshl_add_u64 v[4:5], v[4:5], 0, v[6:7]
	s_movk_i32 s1, 0x4000
	v_add_co_u32_e32 v6, vcc, s1, v4
	s_mov_b32 s1, 0x24000
	s_nop 0
	v_addc_co_u32_e32 v7, vcc, 0, v5, vcc
	global_load_dwordx4 v[60:63], v[4:5], off nt
	global_load_dwordx4 v[64:67], v[6:7], off offset:2048 nt
	v_add_co_u32_e32 v6, vcc, s1, v4
	s_mov_b32 s1, 0x28000
	s_nop 0
	v_addc_co_u32_e32 v7, vcc, 0, v5, vcc
	v_add_co_u32_e32 v8, vcc, s1, v4
	s_mov_b32 s1, 0x48000
	s_nop 0
	v_addc_co_u32_e32 v9, vcc, 0, v5, vcc
	global_load_dwordx4 v[52:55], v[6:7], off nt
	global_load_dwordx4 v[56:59], v[8:9], off offset:2048 nt
	v_add_co_u32_e32 v6, vcc, s1, v4
	s_mov_b32 s1, 0x4c000
	s_nop 0
	v_addc_co_u32_e32 v7, vcc, 0, v5, vcc
	v_add_co_u32_e32 v8, vcc, s1, v4
	s_mov_b32 s1, 0x6c000
	s_nop 0
	v_addc_co_u32_e32 v9, vcc, 0, v5, vcc
	global_load_dwordx4 v[44:47], v[6:7], off nt
	global_load_dwordx4 v[48:51], v[8:9], off offset:2048 nt
	v_add_co_u32_e32 v6, vcc, s1, v4
	s_mov_b32 s1, 0x70000
	s_nop 0
	v_addc_co_u32_e32 v7, vcc, 0, v5, vcc
	v_add_co_u32_e32 v8, vcc, s1, v4
	s_mov_b32 s1, 0x90000
	s_nop 0
	v_addc_co_u32_e32 v9, vcc, 0, v5, vcc
	global_load_dwordx4 v[28:31], v[6:7], off nt
	global_load_dwordx4 v[40:43], v[8:9], off offset:2048 nt
	v_add_co_u32_e32 v6, vcc, s1, v4
	s_mov_b32 s1, 0x94000
	s_nop 0
	v_addc_co_u32_e32 v7, vcc, 0, v5, vcc
	v_add_co_u32_e32 v8, vcc, s1, v4
	s_mov_b32 s1, 0xb4000
	s_nop 0
	v_addc_co_u32_e32 v9, vcc, 0, v5, vcc
	global_load_dwordx4 v[20:23], v[6:7], off nt
	global_load_dwordx4 v[36:39], v[8:9], off offset:2048 nt
	v_add_co_u32_e32 v6, vcc, s1, v4
	s_mov_b32 s1, 0xb8000
	s_nop 0
	v_addc_co_u32_e32 v7, vcc, 0, v5, vcc
	v_add_co_u32_e32 v8, vcc, s1, v4
	v_readlane_b32 s2, v254, 15
	s_nop 0
	v_addc_co_u32_e32 v9, vcc, 0, v5, vcc
	global_load_dwordx4 v[16:19], v[6:7], off nt
	global_load_dwordx4 v[32:35], v[8:9], off offset:2048 nt
	v_add_co_u32_e32 v6, vcc, 0xd8000, v4
	v_readlane_b32 s3, v254, 16
	s_nop 0
	v_addc_co_u32_e32 v7, vcc, 0, v5, vcc
	v_add_co_u32_e32 v12, vcc, 0xdc000, v4
	s_ashr_i32 s9, s8, 31
	s_nop 0
	v_addc_co_u32_e32 v13, vcc, 0, v5, vcc
	global_load_dwordx4 v[8:11], v[6:7], off nt
	global_load_dwordx4 v[24:27], v[12:13], off offset:2048 nt
	v_add_co_u32_e32 v6, vcc, 0xfc000, v4
	s_nop 1
	v_addc_co_u32_e32 v7, vcc, 0, v5, vcc
	v_add_co_u32_e32 v12, vcc, 0x100000, v4
	s_nop 1
	v_addc_co_u32_e32 v13, vcc, 0, v5, vcc
	global_load_dwordx4 v[4:7], v[6:7], off nt
	s_nop 0
	global_load_dwordx4 v[12:15], v[12:13], off offset:2048 nt
	s_andn2_b64 vcc, exec, s[2:3]
	s_cbranch_vccnz .LBB0_1666
	s_lshl_b32 s0, s0, 12
	s_ashr_i32 s1, s0, 31
	s_lshl_b64 s[0:1], s[0:1], 2
	s_add_u32 s2, s60, s0
	s_addc_u32 s3, s61, s1
	s_lshl_b64 s[0:1], s[8:9], 2
	s_add_u32 s0, s2, s0
	s_addc_u32 s1, s3, s1
	v_lshlrev_b32_e32 v103, 2, v72
	global_load_dwordx2 v[116:117], v103, s[0:1]
	global_load_dwordx2 v[118:119], v103, s[0:1] offset:32
	global_load_dwordx2 v[120:121], v103, s[0:1] offset:64
	global_load_dwordx2 v[122:123], v103, s[0:1] offset:96
	global_load_dwordx2 v[124:125], v103, s[0:1] offset:128
	global_load_dwordx2 v[126:127], v103, s[0:1] offset:160
	global_load_dwordx2 v[128:129], v103, s[0:1] offset:192
	global_load_dwordx2 v[130:131], v103, s[0:1] offset:224
	s_waitcnt vmcnt(0)
	v_pk_mul_f32 v[62:63], v[62:63], v[116:117] op_sel_hi:[1,0]
	v_pk_mul_f32 v[60:61], v[60:61], v[116:117] op_sel_hi:[1,0]
	v_pk_mul_f32 v[66:67], v[66:67], v[116:117] op_sel:[0,1]
	v_pk_mul_f32 v[64:65], v[64:65], v[116:117] op_sel:[0,1]
	v_pk_mul_f32 v[54:55], v[54:55], v[118:119] op_sel_hi:[1,0]
	v_pk_mul_f32 v[52:53], v[52:53], v[118:119] op_sel_hi:[1,0]
	v_pk_mul_f32 v[58:59], v[58:59], v[118:119] op_sel:[0,1]
	v_pk_mul_f32 v[56:57], v[56:57], v[118:119] op_sel:[0,1]
	v_pk_mul_f32 v[46:47], v[46:47], v[120:121] op_sel_hi:[1,0]
	v_pk_mul_f32 v[44:45], v[44:45], v[120:121] op_sel_hi:[1,0]
	v_pk_mul_f32 v[50:51], v[50:51], v[120:121] op_sel:[0,1]
	v_pk_mul_f32 v[48:49], v[48:49], v[120:121] op_sel:[0,1]
	v_pk_mul_f32 v[30:31], v[30:31], v[122:123] op_sel_hi:[1,0]
	v_pk_mul_f32 v[28:29], v[28:29], v[122:123] op_sel_hi:[1,0]
	v_pk_mul_f32 v[42:43], v[42:43], v[122:123] op_sel:[0,1]
	v_pk_mul_f32 v[40:41], v[40:41], v[122:123] op_sel:[0,1]
	v_pk_mul_f32 v[22:23], v[22:23], v[124:125] op_sel_hi:[1,0]
	v_pk_mul_f32 v[20:21], v[20:21], v[124:125] op_sel_hi:[1,0]
	v_pk_mul_f32 v[38:39], v[38:39], v[124:125] op_sel:[0,1]
	v_pk_mul_f32 v[36:37], v[36:37], v[124:125] op_sel:[0,1]
	v_pk_mul_f32 v[18:19], v[18:19], v[126:127] op_sel_hi:[1,0]
	v_pk_mul_f32 v[16:17], v[16:17], v[126:127] op_sel_hi:[1,0]
	v_pk_mul_f32 v[34:35], v[34:35], v[126:127] op_sel:[0,1]
	v_pk_mul_f32 v[32:33], v[32:33], v[126:127] op_sel:[0,1]
	v_pk_mul_f32 v[10:11], v[10:11], v[128:129] op_sel_hi:[1,0]
	v_pk_mul_f32 v[8:9], v[8:9], v[128:129] op_sel_hi:[1,0]
	v_pk_mul_f32 v[26:27], v[26:27], v[128:129] op_sel:[0,1]
	v_pk_mul_f32 v[24:25], v[24:25], v[128:129] op_sel:[0,1]
	v_pk_mul_f32 v[6:7], v[6:7], v[130:131] op_sel_hi:[1,0]
	v_pk_mul_f32 v[4:5], v[4:5], v[130:131] op_sel_hi:[1,0]
	v_pk_mul_f32 v[14:15], v[14:15], v[130:131] op_sel:[0,1]
	v_pk_mul_f32 v[12:13], v[12:13], v[130:131] op_sel:[0,1]
	s_branch .LBB0_1666
